# fill_rstd: all units' ssq loads issued first (one wait) instead of a load round trip per unit; barrier release hop removed
# speedup vs baseline: 1.0135x; 1.0135x over previous
.Lsync_last_0:
	s_or_b64 exec, exec, s[12:13]
	s_add_u32 s24, s8, 0x17202400
	s_addc_u32 s25, s9, 0
	v_mov_b32_e32 v7, 0
	v_mov_b32_e32 v8, 1
	global_atomic_add v7, v8, s[24:25]
	global_atomic_add v7, v8, s[24:25] offset:256
	global_atomic_add v7, v8, s[24:25] offset:512
	global_atomic_add v7, v8, s[24:25] offset:768
	global_atomic_add v7, v8, s[24:25] offset:1024
	global_atomic_add v7, v8, s[24:25] offset:1280
	global_atomic_add v7, v8, s[24:25] offset:1536
	global_atomic_add v7, v8, s[24:25] offset:1792
	global_atomic_add v7, v8, s[24:25] offset:2048
	global_atomic_add v7, v8, s[24:25] offset:2304
	global_atomic_add v7, v8, s[24:25] offset:2560
	global_atomic_add v7, v8, s[24:25] offset:2816
	global_atomic_add v7, v8, s[24:25] offset:3072
	global_atomic_add v7, v8, s[24:25] offset:3328
	global_atomic_add v7, v8, s[24:25] offset:3584
	global_atomic_add v7, v8, s[24:25] offset:3840

.LBB0_244:
	v_and_b32_e32 v5, 1, v130
	s_lshl_b32 s31, s6, 2
	s_lshl_b32 s8, s6, 7
	s_lshl_b32 s4, s6, 4
	v_lshlrev_b32_e32 v134, 5, v5
	v_cmp_eq_u32_e64 s[6:7], 0, v5
	v_cvt_f32_ubyte0_e32 v5, s31
	v_rcp_iflag_f32_e32 v5, v5
	s_sub_i32 s19, 0, s31
	v_ashrrev_i32_e32 v4, 1, v130
	s_mov_b32 s9, s61
	v_mul_f32_e32 v5, 0x4f7ffffe, v5
	v_cvt_u32_f32_e32 v5, v5
	s_or_b32 s5, s4, 1
	v_lshl_add_u64 v[2:3], s[82:83], 0, v[134:135]
	s_mov_b64 s[22:23], s[2:3]
	v_readfirstlane_b32 s21, v5
	s_mul_i32 s19, s19, s21
	s_mul_hi_u32 s19, s21, s19
	s_add_i32 s64, s21, s19
	v_readlane_b32 s19, v255, 0
	s_nop 1
	v_lshl_add_u32 v5, v4, 2, s19
	s_waitcnt lgkmcnt(0)
	v_mov_b64_e32 v[6:7], s[8:9]
	v_cmp_ge_i64_e32 vcc, s[22:23], v[6:7]
	s_mov_b64 s[26:27], -1
	s_cbranch_vccnz .Lfrkvq_issued
	s_ashr_i32 s19, s22, 31
	s_lshr_b32 s19, s19, 29
	s_add_i32 s19, s22, s19
	s_ashr_i32 s21, s19, 3
	s_and_b32 s19, s19, -8
	s_sub_i32 s19, s22, s19
	s_cmp_lt_i32 s19, 0
	s_cselect_b32 s24, s5, s4
	s_mul_i32 s19, s24, s19
	s_add_i32 s19, s19, s21
	s_abs_i32 s24, s19
	s_mul_hi_u32 s25, s24, s64
	s_mul_i32 s26, s25, s31
	s_sub_i32 s24, s24, s26
	s_ashr_i32 s21, s19, 31
	s_add_i32 s26, s25, 1
	s_sub_i32 s27, s24, s31
	s_cmp_ge_u32 s24, s31
	s_cselect_b32 s25, s26, s25
	s_cselect_b32 s24, s27, s24
	s_add_i32 s26, s25, 1
	s_cmp_ge_u32 s24, s31
	s_cselect_b32 s24, s26, s25
	s_xor_b32 s24, s24, s21
	s_sub_i32 s21, s24, s21
	s_mul_i32 s24, s21, s31
	s_lshl_b32 s21, s21, 2
	s_sub_i32 s19, s19, s24
	s_sub_i32 s24, 0x80, s21
	s_min_i32 s24, s24, 4
	s_abs_i32 s24, s24
	v_cvt_f32_u32_e32 v6, s24
	s_sub_i32 s26, 0, s24
	s_ashr_i32 s25, s19, 31
	s_abs_i32 s19, s19
	v_rcp_iflag_f32_e32 v6, v6
	s_nop 0
	v_mul_f32_e32 v6, 0x4f7ffffe, v6
	v_cvt_u32_f32_e32 v6, v6
	s_nop 0
	v_readfirstlane_b32 s27, v6
	s_mul_i32 s26, s26, s27
	s_mul_hi_u32 s26, s27, s26
	s_add_i32 s27, s27, s26
	s_mul_hi_u32 s26, s19, s27
	s_mul_i32 s26, s26, s24
	s_sub_i32 s19, s19, s26
	s_sub_i32 s26, s19, s24
	s_cmp_ge_u32 s19, s24
	s_cselect_b32 s19, s26, s19
	s_sub_i32 s26, s19, s24
	s_cmp_ge_u32 s19, s24
	s_cselect_b32 s19, s26, s19
	s_xor_b32 s19, s19, s25
	s_sub_i32 s19, s19, s25
	s_add_i32 s19, s19, s21
	v_lshl_add_u32 v6, s19, 8, v4
	v_ashrrev_i32_e32 v7, 31, v6
	v_lshlrev_b64 v[6:7], 6, v[6:7]
	v_lshl_add_u64 v[10:11], v[2:3], 0, v[6:7]
	global_load_dwordx4 v[14:17], v[10:11], off
	global_load_dwordx4 v[18:21], v[10:11], off offset:16
	s_add_u32 s22, s22, s14
	s_addc_u32 s23, s23, s55
	s_waitcnt lgkmcnt(0)
	v_mov_b64_e32 v[6:7], s[8:9]
	v_cmp_ge_i64_e32 vcc, s[22:23], v[6:7]
	s_mov_b64 s[26:27], -1
	s_cbranch_vccnz .Lfrkvq_issued
	s_ashr_i32 s19, s22, 31
	s_lshr_b32 s19, s19, 29
	s_add_i32 s19, s22, s19
	s_ashr_i32 s21, s19, 3
	s_and_b32 s19, s19, -8
	s_sub_i32 s19, s22, s19
	s_cmp_lt_i32 s19, 0
	s_cselect_b32 s24, s5, s4
	s_mul_i32 s19, s24, s19
	s_add_i32 s19, s19, s21
	s_abs_i32 s24, s19
	s_mul_hi_u32 s25, s24, s64
	s_mul_i32 s26, s25, s31
	s_sub_i32 s24, s24, s26
	s_ashr_i32 s21, s19, 31
	s_add_i32 s26, s25, 1
	s_sub_i32 s27, s24, s31
	s_cmp_ge_u32 s24, s31
	s_cselect_b32 s25, s26, s25
	s_cselect_b32 s24, s27, s24
	s_add_i32 s26, s25, 1
	s_cmp_ge_u32 s24, s31
	s_cselect_b32 s24, s26, s25
	s_xor_b32 s24, s24, s21
	s_sub_i32 s21, s24, s21
	s_mul_i32 s24, s21, s31
	s_lshl_b32 s21, s21, 2
	s_sub_i32 s19, s19, s24
	s_sub_i32 s24, 0x80, s21
	s_min_i32 s24, s24, 4
	s_abs_i32 s24, s24
	v_cvt_f32_u32_e32 v6, s24
	s_sub_i32 s26, 0, s24
	s_ashr_i32 s25, s19, 31
	s_abs_i32 s19, s19
	v_rcp_iflag_f32_e32 v6, v6
	s_nop 0
	v_mul_f32_e32 v6, 0x4f7ffffe, v6
	v_cvt_u32_f32_e32 v6, v6
	s_nop 0
	v_readfirstlane_b32 s27, v6
	s_mul_i32 s26, s26, s27
	s_mul_hi_u32 s26, s27, s26
	s_add_i32 s27, s27, s26
	s_mul_hi_u32 s26, s19, s27
	s_mul_i32 s26, s26, s24
	s_sub_i32 s19, s19, s26
	s_sub_i32 s26, s19, s24
	s_cmp_ge_u32 s19, s24
	s_cselect_b32 s19, s26, s19
	s_sub_i32 s26, s19, s24
	s_cmp_ge_u32 s19, s24
	s_cselect_b32 s19, s26, s19
	s_xor_b32 s19, s19, s25
	s_sub_i32 s19, s19, s25
	s_add_i32 s19, s19, s21
	v_lshl_add_u32 v6, s19, 8, v4
	v_ashrrev_i32_e32 v7, 31, v6
	v_lshlrev_b64 v[6:7], 6, v[6:7]
	v_lshl_add_u64 v[10:11], v[2:3], 0, v[6:7]
	global_load_dwordx4 v[22:25], v[10:11], off
	global_load_dwordx4 v[26:29], v[10:11], off offset:16
	s_add_u32 s22, s22, s14
	s_addc_u32 s23, s23, s55
	s_waitcnt lgkmcnt(0)
	v_mov_b64_e32 v[6:7], s[8:9]
	v_cmp_ge_i64_e32 vcc, s[22:23], v[6:7]
	s_mov_b64 s[26:27], -1
	s_cbranch_vccnz .Lfrkvq_issued
	s_ashr_i32 s19, s22, 31
	s_lshr_b32 s19, s19, 29
	s_add_i32 s19, s22, s19
	s_ashr_i32 s21, s19, 3
	s_and_b32 s19, s19, -8
	s_sub_i32 s19, s22, s19
	s_cmp_lt_i32 s19, 0
	s_cselect_b32 s24, s5, s4
	s_mul_i32 s19, s24, s19
	s_add_i32 s19, s19, s21
	s_abs_i32 s24, s19
	s_mul_hi_u32 s25, s24, s64
	s_mul_i32 s26, s25, s31
	s_sub_i32 s24, s24, s26
	s_ashr_i32 s21, s19, 31
	s_add_i32 s26, s25, 1
	s_sub_i32 s27, s24, s31
	s_cmp_ge_u32 s24, s31
	s_cselect_b32 s25, s26, s25
	s_cselect_b32 s24, s27, s24
	s_add_i32 s26, s25, 1
	s_cmp_ge_u32 s24, s31
	s_cselect_b32 s24, s26, s25
	s_xor_b32 s24, s24, s21
	s_sub_i32 s21, s24, s21
	s_mul_i32 s24, s21, s31
	s_lshl_b32 s21, s21, 2
	s_sub_i32 s19, s19, s24
	s_sub_i32 s24, 0x80, s21
	s_min_i32 s24, s24, 4
	s_abs_i32 s24, s24
	v_cvt_f32_u32_e32 v6, s24
	s_sub_i32 s26, 0, s24
	s_ashr_i32 s25, s19, 31
	s_abs_i32 s19, s19
	v_rcp_iflag_f32_e32 v6, v6
	s_nop 0
	v_mul_f32_e32 v6, 0x4f7ffffe, v6
	v_cvt_u32_f32_e32 v6, v6
	s_nop 0
	v_readfirstlane_b32 s27, v6
	s_mul_i32 s26, s26, s27
	s_mul_hi_u32 s26, s27, s26
	s_add_i32 s27, s27, s26
	s_mul_hi_u32 s26, s19, s27
	s_mul_i32 s26, s26, s24
	s_sub_i32 s19, s19, s26
	s_sub_i32 s26, s19, s24
	s_cmp_ge_u32 s19, s24
	s_cselect_b32 s19, s26, s19
	s_sub_i32 s26, s19, s24
	s_cmp_ge_u32 s19, s24
	s_cselect_b32 s19, s26, s19
	s_xor_b32 s19, s19, s25
	s_sub_i32 s19, s19, s25
	s_add_i32 s19, s19, s21
	v_lshl_add_u32 v6, s19, 8, v4
	v_ashrrev_i32_e32 v7, 31, v6
	v_lshlrev_b64 v[6:7], 6, v[6:7]
	v_lshl_add_u64 v[10:11], v[2:3], 0, v[6:7]
	global_load_dwordx4 v[30:33], v[10:11], off
	global_load_dwordx4 v[34:37], v[10:11], off offset:16
	s_add_u32 s22, s22, s14
	s_addc_u32 s23, s23, s55
.Lfrkvq_issued:
	s_waitcnt vmcnt(0)
	s_mov_b64 s[22:23], s[2:3]
	s_waitcnt lgkmcnt(0)
	v_mov_b64_e32 v[6:7], s[8:9]
	v_cmp_ge_i64_e32 vcc, s[22:23], v[6:7]
	s_mov_b64 s[26:27], -1
	s_cbranch_vccnz .Lfrkvq_done
	v_pk_add_f32 v[16:17], v[16:17], v[20:21]
	v_pk_add_f32 v[14:15], v[14:15], v[18:19]
	v_cmp_lt_i32_e32 vcc, v172, v171
	v_add_f32_e32 v6, v14, v15
	v_add_f32_e32 v7, v16, v17
	v_add_f32_e32 v6, v6, v7
	v_cndmask_b32_e32 v7, v170, v172, vcc
	v_lshlrev_b32_e32 v7, 2, v7
	ds_bpermute_b32 v7, v7, v6
	s_and_saveexec_b64 s[26:27], s[6:7]
	s_waitcnt lgkmcnt(0)
	v_add_f32_e32 v6, v6, v7
	v_fmamk_f32 v6, v6, 0x3a800000, v166
	v_rsq_f32_e32 v6, v6
	ds_write_b32 v5, v6
	s_or_b64 exec, exec, s[26:27]
	s_add_u32 s22, s22, s14
	s_addc_u32 s23, s23, s55
	s_waitcnt lgkmcnt(0)
	v_mov_b64_e32 v[6:7], s[8:9]
	v_cmp_ge_i64_e32 vcc, s[22:23], v[6:7]
	s_mov_b64 s[26:27], -1
	s_cbranch_vccnz .Lfrkvq_done
	v_pk_add_f32 v[24:25], v[24:25], v[28:29]
	v_pk_add_f32 v[22:23], v[22:23], v[26:27]
	v_cmp_lt_i32_e32 vcc, v172, v171
	v_add_f32_e32 v6, v22, v23
	v_add_f32_e32 v7, v24, v25
	v_add_f32_e32 v6, v6, v7
	v_cndmask_b32_e32 v7, v170, v172, vcc
	v_lshlrev_b32_e32 v7, 2, v7
	ds_bpermute_b32 v7, v7, v6
	s_and_saveexec_b64 s[26:27], s[6:7]
	s_waitcnt lgkmcnt(0)
	v_add_f32_e32 v6, v6, v7
	v_fmamk_f32 v6, v6, 0x3a800000, v166
	v_rsq_f32_e32 v6, v6
	ds_write_b32 v5, v6 offset:1024
	s_or_b64 exec, exec, s[26:27]
	s_add_u32 s22, s22, s14
	s_addc_u32 s23, s23, s55
	s_waitcnt lgkmcnt(0)
	v_mov_b64_e32 v[6:7], s[8:9]
	v_cmp_ge_i64_e32 vcc, s[22:23], v[6:7]
	s_mov_b64 s[26:27], -1
	s_cbranch_vccnz .Lfrkvq_done
	v_pk_add_f32 v[32:33], v[32:33], v[36:37]
	v_pk_add_f32 v[30:31], v[30:31], v[34:35]
	v_cmp_lt_i32_e32 vcc, v172, v171
	v_add_f32_e32 v6, v30, v31
	v_add_f32_e32 v7, v32, v33
	v_add_f32_e32 v6, v6, v7
	v_cndmask_b32_e32 v7, v170, v172, vcc
	v_lshlrev_b32_e32 v7, 2, v7
	ds_bpermute_b32 v7, v7, v6
	s_and_saveexec_b64 s[26:27], s[6:7]
	s_waitcnt lgkmcnt(0)
	v_add_f32_e32 v6, v6, v7
	v_fmamk_f32 v6, v6, 0x3a800000, v166
	v_rsq_f32_e32 v6, v6
	ds_write_b32 v5, v6 offset:2048
	s_or_b64 exec, exec, s[26:27]
	s_add_u32 s22, s22, s14
	s_addc_u32 s23, s23, s55
.Lfrkvq_done:
.LBB0_250:
	s_cmp_ge_i32 s2, s8
	v_readfirstlane_b32 s6, v130
	s_waitcnt vmcnt(0) lgkmcnt(0)
	s_barrier
	s_cbranch_scc1 .LBB0_266
	v_lshlrev_b32_e32 v2, 4, v130
	v_add_u32_e32 v3, 0x2000, v2
	v_ashrrev_i32_e32 v4, 31, v3
	v_lshrrev_b32_e32 v4, 22, v4
	v_add_u32_e32 v4, v3, v4
	v_ashrrev_i32_e32 v10, 10, v4
	v_mul_i32_i24_e32 v4, 0x400, v10
	v_sub_u32_e32 v3, v3, v4
	v_lshrrev_b32_e32 v4, 4, v3
	v_bitop3_b32 v3, v4, v3, 32 bitop3:0x6c
	v_ashrrev_i32_e32 v4, 31, v3
	v_lshrrev_b32_e32 v4, 26, v4
	v_add_u32_e32 v4, v3, v4
	v_lshlrev_b32_e32 v5, 3, v10
	v_ashrrev_i32_e32 v11, 6, v4
	v_and_b32_e32 v5, -16, v5
	v_add_u32_e32 v5, v11, v5
	s_add_u32 s19, s82, s12
	v_and_b32_e32 v6, 3, v11
	s_mov_b32 s12, 0x1fffe0
	v_lshrrev_b32_e32 v7, 2, v5
	v_lshlrev_b32_e32 v8, 1, v5
	v_and_b32_e32 v4, 0xc0, v4
	v_and_or_b32 v6, v5, s12, v6
	v_and_b32_e32 v7, 4, v7
	v_and_b32_e32 v8, 24, v8
	v_sub_u32_e32 v3, v3, v4
	v_or3_b32 v6, v6, v7, v8
	v_lshlrev_b32_e32 v7, 5, v10
	v_ashrrev_i16_sdwa v3, v169, sext(v3) dst_sel:DWORD dst_unused:UNUSED_PAD src0_sel:DWORD src1_sel:BYTE_0
	v_and_b32_e32 v7, 32, v7
	v_bfe_i32 v12, v3, 0, 16
	v_add_lshl_u32 v3, v7, v12, 1
	v_lshl_add_u32 v132, v6, 11, v3
	v_lshl_add_u32 v144, v5, 11, v3
	v_bfe_i32 v3, v130, 27, 1
	v_lshrrev_b32_e32 v3, 22, v3
	v_add_u32_e32 v3, v2, v3
	v_and_b32_e32 v3, 0xfffffc00, v3
	v_sub_u32_e32 v2, v2, v3
	v_lshrrev_b32_e32 v3, 4, v2
	v_ashrrev_i32_e32 v4, 31, v130
	v_bitop3_b32 v2, v3, v2, 32 bitop3:0x6c
	v_lshrrev_b32_e32 v4, 26, v4
	v_ashrrev_i32_e32 v3, 31, v2
	v_add_u32_e32 v4, v130, v4
	v_lshrrev_b32_e32 v3, 26, v3
	v_ashrrev_i32_e32 v14, 6, v4
	v_add_u32_e32 v3, v2, v3
	v_lshlrev_b32_e32 v4, 3, v14
	v_ashrrev_i32_e32 v13, 6, v3
	v_and_b32_e32 v4, -16, v4
	v_add_u32_e32 v4, v13, v4
	v_and_b32_e32 v5, 3, v13
	s_addc_u32 s62, s83, s13
	s_ashr_i32 s21, s6, 6
	v_and_or_b32 v5, v4, s12, v5
	v_readlane_b32 s12, v254, 18
	s_ashr_i32 s7, s6, 8
	s_lshl_b32 s65, s21, 10
	v_readlane_b32 s13, v254, 19
	s_and_b64 s[12:13], s[12:13], exec
	s_cselect_b32 s12, s5, s4
	v_readlane_b32 s13, v254, 29
	s_mul_i32 s12, s12, s13
	v_readlane_b32 s13, v254, 30
	s_add_i32 s12, s12, s13
	s_abs_i32 s22, s12
	s_mul_hi_u32 s23, s22, s64
	s_mul_i32 s24, s23, s31
	s_sub_i32 s22, s22, s24
	s_ashr_i32 s13, s12, 31
	s_add_i32 s24, s23, 1
	s_sub_i32 s25, s22, s31
	s_cmp_ge_u32 s22, s31
	s_cselect_b32 s23, s24, s23
	s_cselect_b32 s22, s25, s22
	s_add_i32 s24, s23, 1
	s_cmp_ge_u32 s22, s31
	s_cselect_b32 s22, s24, s23
	s_xor_b32 s22, s22, s13
	s_sub_i32 s13, s22, s13
	s_lshl_b32 s22, s13, 2
	v_and_b32_e32 v3, 0xc0, v3
	s_sub_i32 s23, 0x80, s22
	v_sub_u32_e32 v2, v2, v3
	s_min_i32 s23, s23, 4
	v_ashrrev_i16_sdwa v2, v169, sext(v2) dst_sel:DWORD dst_unused:UNUSED_PAD src0_sel:DWORD src1_sel:BYTE_0
	s_abs_i32 s24, s23
	v_bfe_i32 v15, v2, 0, 16
	v_cvt_f32_u32_e32 v2, s24
	s_sub_i32 s26, 0, s24
	s_mul_i32 s13, s13, s31
	s_sub_i32 s12, s12, s13
	v_rcp_iflag_f32_e32 v2, v2
	s_abs_i32 s25, s12
	s_xor_b32 s13, s12, s23
	s_ashr_i32 s13, s13, 31
	v_mul_f32_e32 v2, 0x4f7ffffe, v2
	v_cvt_u32_f32_e32 v2, v2
	v_lshrrev_b32_e32 v6, 2, v4
	v_lshlrev_b32_e32 v7, 1, v4
	v_and_b32_e32 v6, 4, v6
	v_readfirstlane_b32 s27, v2
	s_mul_i32 s26, s26, s27
	s_mul_hi_u32 s26, s27, s26
	s_add_i32 s27, s27, s26
	s_mul_hi_u32 s26, s25, s27
	s_mul_i32 s27, s26, s24
	s_sub_i32 s25, s25, s27
	s_add_i32 s27, s26, 1
	s_sub_i32 s30, s25, s24
	s_cmp_ge_u32 s25, s24
	s_cselect_b32 s26, s27, s26
	s_cselect_b32 s25, s30, s25
	s_add_i32 s27, s26, 1
	s_cmp_ge_u32 s25, s24
	s_cselect_b32 s24, s27, s26
	s_xor_b32 s24, s24, s13
	s_sub_i32 s96, s24, s13
	s_mul_i32 s13, s96, s23
	s_sub_i32 s12, s12, s13
	s_add_i32 s26, s12, s22
	v_and_b32_e32 v7, 24, v7
	s_ashr_i32 s27, s26, 31
	s_ashr_i32 s97, s96, 31
	v_or3_b32 v5, v5, v6, v7
	v_lshlrev_b32_e32 v6, 5, v14
	s_lshl_b64 s[12:13], s[26:27], 19
	s_lshl_b64 s[22:23], s[96:97], 19
	v_and_b32_e32 v6, 32, v6
	s_add_u32 s50, s19, s22
	v_add_lshl_u32 v3, v6, v15, 1
	s_addc_u32 s51, s62, s23
	s_add_i32 s27, s65, 0
	v_lshl_add_u32 v146, v5, 11, v3
	s_add_i32 m0, s27, 0x10000
	v_lshl_add_u32 v148, v4, 11, v3
	global_load_lds_dwordx4 v146, s[50:51]
	s_add_i32 m0, s27, 0x12000
	s_add_u32 s22, s50, 0x40000
	global_load_lds_dwordx4 v132, s[50:51]
	s_addc_u32 s23, s51, 0
	s_add_i32 m0, s27, 0x14000
	v_mov_b32_e32 v147, v135
	global_load_lds_dwordx4 v146, s[22:23]
	s_add_i32 m0, s27, 0x16000
	s_add_u32 s98, s78, s12
	s_addc_u32 s99, s79, s13
	s_add_i32 s74, s27, 0x2000
	global_load_lds_dwordx4 v132, s[22:23]
	s_mov_b32 m0, s27
	s_add_u32 s12, s98, 0x40000
	global_load_lds_dwordx4 v148, s[98:99]
	s_mov_b32 m0, s74
	s_addc_u32 s13, s99, 0
	s_add_i32 s75, s27, 0x4000
	global_load_lds_dwordx4 v144, s[98:99]
	s_mov_b32 m0, s75
	s_add_i32 s97, s27, 0x6000
	global_load_lds_dwordx4 v148, s[12:13]
	s_mov_b32 m0, s97
	v_mov_b32_e32 v133, v135
	global_load_lds_dwordx4 v144, s[12:13]
	v_mov_b32_e32 v149, v135
	v_mov_b32_e32 v145, v135
	s_cmp_eq_u32 s7, 1
	v_lshl_add_u64 v[8:9], s[50:51], 0, v[146:147]
	v_lshl_add_u64 v[6:7], s[50:51], 0, v[132:133]
	v_lshl_add_u64 v[2:3], s[98:99], 0, v[148:149]
	s_cselect_b64 s[12:13], -1, 0
	s_cmp_lg_u32 s7, 1
	v_lshl_add_u64 v[4:5], s[98:99], 0, v[144:145]
	s_cbranch_scc1 .LBB0_253
	s_barrier

.LBB0_267:
	s_andn2_b64 vcc, exec, s[6:7]
	s_cbranch_vccnz .LBB0_290
	v_and_b32_e32 v5, 1, v130
	v_ashrrev_i32_e32 v4, 1, v130
	v_lshlrev_b32_e32 v134, 5, v5
	v_readlane_b32 s4, v255, 0
	v_lshl_add_u64 v[2:3], s[82:83], 0, v[134:135]
	v_cmp_eq_u32_e64 s[6:7], 0, v5
	v_lshl_add_u32 v5, v4, 2, s4
	s_mov_b64 s[8:9], s[2:3]
	v_cmp_gt_i64_e32 vcc, s[8:9], v[136:137]
	s_mov_b64 s[12:13], -1
	s_cbranch_vccnz .Lfrup_issued
	s_ashr_i32 s4, s8, 31
	s_lshr_b32 s4, s4, 29
	s_add_i32 s4, s8, s4
	s_ashr_i32 s5, s4, 3
	s_and_b32 s4, s4, -8
	s_sub_i32 s4, s8, s4
	s_cmp_lt_i32 s4, 0
	s_cselect_b32 s12, s43, 0x160
	s_mul_i32 s4, s4, s12
	s_add_i32 s4, s4, s5
	s_mul_hi_i32 s5, s4, 0x2e8ba2e9
	s_lshr_b32 s12, s5, 31
	s_ashr_i32 s5, s5, 4
	s_add_i32 s5, s5, s12
	s_mul_i32 s12, s5, 0x58
	s_lshl_b32 s5, s5, 2
	s_sub_i32 s4, s4, s12
	s_sub_i32 s12, 0x80, s5
	s_min_i32 s12, s12, 4
	s_abs_i32 s12, s12
	v_cvt_f32_u32_e32 v6, s12
	s_sub_i32 s19, 0, s12
	s_ashr_i32 s13, s4, 31
	s_abs_i32 s4, s4
	v_rcp_iflag_f32_e32 v6, v6
	s_nop 0
	v_mul_f32_e32 v6, 0x4f7ffffe, v6
	v_cvt_u32_f32_e32 v6, v6
	s_nop 0
	v_readfirstlane_b32 s21, v6
	s_mul_i32 s19, s19, s21
	s_mul_hi_u32 s19, s21, s19
	s_add_i32 s21, s21, s19
	s_mul_hi_u32 s19, s4, s21
	s_mul_i32 s19, s19, s12
	s_sub_i32 s4, s4, s19
	s_sub_i32 s19, s4, s12
	s_cmp_ge_u32 s4, s12
	s_cselect_b32 s4, s19, s4
	s_sub_i32 s19, s4, s12
	s_cmp_ge_u32 s4, s12
	s_cselect_b32 s4, s19, s4
	s_xor_b32 s4, s4, s13
	s_sub_i32 s4, s4, s13
	s_add_i32 s5, s5, s4
	v_lshl_add_u32 v6, s5, 8, v4
	s_waitcnt lgkmcnt(0)
	v_ashrrev_i32_e32 v7, 31, v6
	v_lshlrev_b64 v[6:7], 6, v[6:7]
	v_lshl_add_u64 v[10:11], v[2:3], 0, v[6:7]
	global_load_dwordx4 v[14:17], v[10:11], off
	global_load_dwordx4 v[18:21], v[10:11], off offset:16
	s_add_u32 s8, s8, s14
	s_addc_u32 s9, s9, s55
	v_cmp_gt_i64_e32 vcc, s[8:9], v[136:137]
	s_mov_b64 s[12:13], -1
	s_cbranch_vccnz .Lfrup_issued
	s_ashr_i32 s4, s8, 31
	s_lshr_b32 s4, s4, 29
	s_add_i32 s4, s8, s4
	s_ashr_i32 s5, s4, 3
	s_and_b32 s4, s4, -8
	s_sub_i32 s4, s8, s4
	s_cmp_lt_i32 s4, 0
	s_cselect_b32 s12, s43, 0x160
	s_mul_i32 s4, s4, s12
	s_add_i32 s4, s4, s5
	s_mul_hi_i32 s5, s4, 0x2e8ba2e9
	s_lshr_b32 s12, s5, 31
	s_ashr_i32 s5, s5, 4
	s_add_i32 s5, s5, s12
	s_mul_i32 s12, s5, 0x58
	s_lshl_b32 s5, s5, 2
	s_sub_i32 s4, s4, s12
	s_sub_i32 s12, 0x80, s5
	s_min_i32 s12, s12, 4
	s_abs_i32 s12, s12
	v_cvt_f32_u32_e32 v6, s12
	s_sub_i32 s19, 0, s12
	s_ashr_i32 s13, s4, 31
	s_abs_i32 s4, s4
	v_rcp_iflag_f32_e32 v6, v6
	s_nop 0
	v_mul_f32_e32 v6, 0x4f7ffffe, v6
	v_cvt_u32_f32_e32 v6, v6
	s_nop 0
	v_readfirstlane_b32 s21, v6
	s_mul_i32 s19, s19, s21
	s_mul_hi_u32 s19, s21, s19
	s_add_i32 s21, s21, s19
	s_mul_hi_u32 s19, s4, s21
	s_mul_i32 s19, s19, s12
	s_sub_i32 s4, s4, s19
	s_sub_i32 s19, s4, s12
	s_cmp_ge_u32 s4, s12
	s_cselect_b32 s4, s19, s4
	s_sub_i32 s19, s4, s12
	s_cmp_ge_u32 s4, s12
	s_cselect_b32 s4, s19, s4
	s_xor_b32 s4, s4, s13
	s_sub_i32 s4, s4, s13
	s_add_i32 s5, s5, s4
	v_lshl_add_u32 v6, s5, 8, v4
	s_waitcnt lgkmcnt(0)
	v_ashrrev_i32_e32 v7, 31, v6
	v_lshlrev_b64 v[6:7], 6, v[6:7]
	v_lshl_add_u64 v[10:11], v[2:3], 0, v[6:7]
	global_load_dwordx4 v[22:25], v[10:11], off
	global_load_dwordx4 v[26:29], v[10:11], off offset:16
	s_add_u32 s8, s8, s14
	s_addc_u32 s9, s9, s55
	v_cmp_gt_i64_e32 vcc, s[8:9], v[136:137]
	s_mov_b64 s[12:13], -1
	s_cbranch_vccnz .Lfrup_issued
	s_ashr_i32 s4, s8, 31
	s_lshr_b32 s4, s4, 29
	s_add_i32 s4, s8, s4
	s_ashr_i32 s5, s4, 3
	s_and_b32 s4, s4, -8
	s_sub_i32 s4, s8, s4
	s_cmp_lt_i32 s4, 0
	s_cselect_b32 s12, s43, 0x160
	s_mul_i32 s4, s4, s12
	s_add_i32 s4, s4, s5
	s_mul_hi_i32 s5, s4, 0x2e8ba2e9
	s_lshr_b32 s12, s5, 31
	s_ashr_i32 s5, s5, 4
	s_add_i32 s5, s5, s12
	s_mul_i32 s12, s5, 0x58
	s_lshl_b32 s5, s5, 2
	s_sub_i32 s4, s4, s12
	s_sub_i32 s12, 0x80, s5
	s_min_i32 s12, s12, 4
	s_abs_i32 s12, s12
	v_cvt_f32_u32_e32 v6, s12
	s_sub_i32 s19, 0, s12
	s_ashr_i32 s13, s4, 31
	s_abs_i32 s4, s4
	v_rcp_iflag_f32_e32 v6, v6
	s_nop 0
	v_mul_f32_e32 v6, 0x4f7ffffe, v6
	v_cvt_u32_f32_e32 v6, v6
	s_nop 0
	v_readfirstlane_b32 s21, v6
	s_mul_i32 s19, s19, s21
	s_mul_hi_u32 s19, s21, s19
	s_add_i32 s21, s21, s19
	s_mul_hi_u32 s19, s4, s21
	s_mul_i32 s19, s19, s12
	s_sub_i32 s4, s4, s19
	s_sub_i32 s19, s4, s12
	s_cmp_ge_u32 s4, s12
	s_cselect_b32 s4, s19, s4
	s_sub_i32 s19, s4, s12
	s_cmp_ge_u32 s4, s12
	s_cselect_b32 s4, s19, s4
	s_xor_b32 s4, s4, s13
	s_sub_i32 s4, s4, s13
	s_add_i32 s5, s5, s4
	v_lshl_add_u32 v6, s5, 8, v4
	s_waitcnt lgkmcnt(0)
	v_ashrrev_i32_e32 v7, 31, v6
	v_lshlrev_b64 v[6:7], 6, v[6:7]
	v_lshl_add_u64 v[10:11], v[2:3], 0, v[6:7]
	global_load_dwordx4 v[30:33], v[10:11], off
	global_load_dwordx4 v[34:37], v[10:11], off offset:16
	s_add_u32 s8, s8, s14
	s_addc_u32 s9, s9, s55
	v_cmp_gt_i64_e32 vcc, s[8:9], v[136:137]
	s_mov_b64 s[12:13], -1
	s_cbranch_vccnz .Lfrup_issued
	s_ashr_i32 s4, s8, 31
	s_lshr_b32 s4, s4, 29
	s_add_i32 s4, s8, s4
	s_ashr_i32 s5, s4, 3
	s_and_b32 s4, s4, -8
	s_sub_i32 s4, s8, s4
	s_cmp_lt_i32 s4, 0
	s_cselect_b32 s12, s43, 0x160
	s_mul_i32 s4, s4, s12
	s_add_i32 s4, s4, s5
	s_mul_hi_i32 s5, s4, 0x2e8ba2e9
	s_lshr_b32 s12, s5, 31
	s_ashr_i32 s5, s5, 4
	s_add_i32 s5, s5, s12
	s_mul_i32 s12, s5, 0x58
	s_lshl_b32 s5, s5, 2
	s_sub_i32 s4, s4, s12
	s_sub_i32 s12, 0x80, s5
	s_min_i32 s12, s12, 4
	s_abs_i32 s12, s12
	v_cvt_f32_u32_e32 v6, s12
	s_sub_i32 s19, 0, s12
	s_ashr_i32 s13, s4, 31
	s_abs_i32 s4, s4
	v_rcp_iflag_f32_e32 v6, v6
	s_nop 0
	v_mul_f32_e32 v6, 0x4f7ffffe, v6
	v_cvt_u32_f32_e32 v6, v6
	s_nop 0
	v_readfirstlane_b32 s21, v6
	s_mul_i32 s19, s19, s21
	s_mul_hi_u32 s19, s21, s19
	s_add_i32 s21, s21, s19
	s_mul_hi_u32 s19, s4, s21
	s_mul_i32 s19, s19, s12
	s_sub_i32 s4, s4, s19
	s_sub_i32 s19, s4, s12
	s_cmp_ge_u32 s4, s12
	s_cselect_b32 s4, s19, s4
	s_sub_i32 s19, s4, s12
	s_cmp_ge_u32 s4, s12
	s_cselect_b32 s4, s19, s4
	s_xor_b32 s4, s4, s13
	s_sub_i32 s4, s4, s13
	s_add_i32 s5, s5, s4
	v_lshl_add_u32 v6, s5, 8, v4
	s_waitcnt lgkmcnt(0)
	v_ashrrev_i32_e32 v7, 31, v6
	v_lshlrev_b64 v[6:7], 6, v[6:7]
	v_lshl_add_u64 v[10:11], v[2:3], 0, v[6:7]
	global_load_dwordx4 v[38:41], v[10:11], off
	global_load_dwordx4 v[42:45], v[10:11], off offset:16
	s_add_u32 s8, s8, s14
	s_addc_u32 s9, s9, s55
	v_cmp_gt_i64_e32 vcc, s[8:9], v[136:137]
	s_mov_b64 s[12:13], -1
	s_cbranch_vccnz .Lfrup_issued
	s_ashr_i32 s4, s8, 31
	s_lshr_b32 s4, s4, 29
	s_add_i32 s4, s8, s4
	s_ashr_i32 s5, s4, 3
	s_and_b32 s4, s4, -8
	s_sub_i32 s4, s8, s4
	s_cmp_lt_i32 s4, 0
	s_cselect_b32 s12, s43, 0x160
	s_mul_i32 s4, s4, s12
	s_add_i32 s4, s4, s5
	s_mul_hi_i32 s5, s4, 0x2e8ba2e9
	s_lshr_b32 s12, s5, 31
	s_ashr_i32 s5, s5, 4
	s_add_i32 s5, s5, s12
	s_mul_i32 s12, s5, 0x58
	s_lshl_b32 s5, s5, 2
	s_sub_i32 s4, s4, s12
	s_sub_i32 s12, 0x80, s5
	s_min_i32 s12, s12, 4
	s_abs_i32 s12, s12
	v_cvt_f32_u32_e32 v6, s12
	s_sub_i32 s19, 0, s12
	s_ashr_i32 s13, s4, 31
	s_abs_i32 s4, s4
	v_rcp_iflag_f32_e32 v6, v6
	s_nop 0
	v_mul_f32_e32 v6, 0x4f7ffffe, v6
	v_cvt_u32_f32_e32 v6, v6
	s_nop 0
	v_readfirstlane_b32 s21, v6
	s_mul_i32 s19, s19, s21
	s_mul_hi_u32 s19, s21, s19
	s_add_i32 s21, s21, s19
	s_mul_hi_u32 s19, s4, s21
	s_mul_i32 s19, s19, s12
	s_sub_i32 s4, s4, s19
	s_sub_i32 s19, s4, s12
	s_cmp_ge_u32 s4, s12
	s_cselect_b32 s4, s19, s4
	s_sub_i32 s19, s4, s12
	s_cmp_ge_u32 s4, s12
	s_cselect_b32 s4, s19, s4
	s_xor_b32 s4, s4, s13
	s_sub_i32 s4, s4, s13
	s_add_i32 s5, s5, s4
	v_lshl_add_u32 v6, s5, 8, v4
	s_waitcnt lgkmcnt(0)
	v_ashrrev_i32_e32 v7, 31, v6
	v_lshlrev_b64 v[6:7], 6, v[6:7]
	v_lshl_add_u64 v[10:11], v[2:3], 0, v[6:7]
	global_load_dwordx4 v[46:49], v[10:11], off
	global_load_dwordx4 v[50:53], v[10:11], off offset:16
	s_add_u32 s8, s8, s14
	s_addc_u32 s9, s9, s55
	v_cmp_gt_i64_e32 vcc, s[8:9], v[136:137]
	s_mov_b64 s[12:13], -1
	s_cbranch_vccnz .Lfrup_issued
	s_ashr_i32 s4, s8, 31
	s_lshr_b32 s4, s4, 29
	s_add_i32 s4, s8, s4
	s_ashr_i32 s5, s4, 3
	s_and_b32 s4, s4, -8
	s_sub_i32 s4, s8, s4
	s_cmp_lt_i32 s4, 0
	s_cselect_b32 s12, s43, 0x160
	s_mul_i32 s4, s4, s12
	s_add_i32 s4, s4, s5
	s_mul_hi_i32 s5, s4, 0x2e8ba2e9
	s_lshr_b32 s12, s5, 31
	s_ashr_i32 s5, s5, 4
	s_add_i32 s5, s5, s12
	s_mul_i32 s12, s5, 0x58
	s_lshl_b32 s5, s5, 2
	s_sub_i32 s4, s4, s12
	s_sub_i32 s12, 0x80, s5
	s_min_i32 s12, s12, 4
	s_abs_i32 s12, s12
	v_cvt_f32_u32_e32 v6, s12
	s_sub_i32 s19, 0, s12
	s_ashr_i32 s13, s4, 31
	s_abs_i32 s4, s4
	v_rcp_iflag_f32_e32 v6, v6
	s_nop 0
	v_mul_f32_e32 v6, 0x4f7ffffe, v6
	v_cvt_u32_f32_e32 v6, v6
	s_nop 0
	v_readfirstlane_b32 s21, v6
	s_mul_i32 s19, s19, s21
	s_mul_hi_u32 s19, s21, s19
	s_add_i32 s21, s21, s19
	s_mul_hi_u32 s19, s4, s21
	s_mul_i32 s19, s19, s12
	s_sub_i32 s4, s4, s19
	s_sub_i32 s19, s4, s12
	s_cmp_ge_u32 s4, s12
	s_cselect_b32 s4, s19, s4
	s_sub_i32 s19, s4, s12
	s_cmp_ge_u32 s4, s12
	s_cselect_b32 s4, s19, s4
	s_xor_b32 s4, s4, s13
	s_sub_i32 s4, s4, s13
	s_add_i32 s5, s5, s4
	v_lshl_add_u32 v6, s5, 8, v4
	s_waitcnt lgkmcnt(0)
	v_ashrrev_i32_e32 v7, 31, v6
	v_lshlrev_b64 v[6:7], 6, v[6:7]
	v_lshl_add_u64 v[10:11], v[2:3], 0, v[6:7]
	global_load_dwordx4 v[54:57], v[10:11], off
	global_load_dwordx4 v[58:61], v[10:11], off offset:16
	s_add_u32 s8, s8, s14
	s_addc_u32 s9, s9, s55
	v_cmp_gt_i64_e32 vcc, s[8:9], v[136:137]
	s_mov_b64 s[12:13], -1
	s_cbranch_vccnz .Lfrup_issued
	s_ashr_i32 s4, s8, 31
	s_lshr_b32 s4, s4, 29
	s_add_i32 s4, s8, s4
	s_ashr_i32 s5, s4, 3
	s_and_b32 s4, s4, -8
	s_sub_i32 s4, s8, s4
	s_cmp_lt_i32 s4, 0
	s_cselect_b32 s12, s43, 0x160
	s_mul_i32 s4, s4, s12
	s_add_i32 s4, s4, s5
	s_mul_hi_i32 s5, s4, 0x2e8ba2e9
	s_lshr_b32 s12, s5, 31
	s_ashr_i32 s5, s5, 4
	s_add_i32 s5, s5, s12
	s_mul_i32 s12, s5, 0x58
	s_lshl_b32 s5, s5, 2
	s_sub_i32 s4, s4, s12
	s_sub_i32 s12, 0x80, s5
	s_min_i32 s12, s12, 4
	s_abs_i32 s12, s12
	v_cvt_f32_u32_e32 v6, s12
	s_sub_i32 s19, 0, s12
	s_ashr_i32 s13, s4, 31
	s_abs_i32 s4, s4
	v_rcp_iflag_f32_e32 v6, v6
	s_nop 0
	v_mul_f32_e32 v6, 0x4f7ffffe, v6
	v_cvt_u32_f32_e32 v6, v6
	s_nop 0
	v_readfirstlane_b32 s21, v6
	s_mul_i32 s19, s19, s21
	s_mul_hi_u32 s19, s21, s19
	s_add_i32 s21, s21, s19
	s_mul_hi_u32 s19, s4, s21
	s_mul_i32 s19, s19, s12
	s_sub_i32 s4, s4, s19
	s_sub_i32 s19, s4, s12
	s_cmp_ge_u32 s4, s12
	s_cselect_b32 s4, s19, s4
	s_sub_i32 s19, s4, s12
	s_cmp_ge_u32 s4, s12
	s_cselect_b32 s4, s19, s4
	s_xor_b32 s4, s4, s13
	s_sub_i32 s4, s4, s13
	s_add_i32 s5, s5, s4
	v_lshl_add_u32 v6, s5, 8, v4
	s_waitcnt lgkmcnt(0)
	v_ashrrev_i32_e32 v7, 31, v6
	v_lshlrev_b64 v[6:7], 6, v[6:7]
	v_lshl_add_u64 v[10:11], v[2:3], 0, v[6:7]
	global_load_dwordx4 v[62:65], v[10:11], off
	global_load_dwordx4 v[66:69], v[10:11], off offset:16
	s_add_u32 s8, s8, s14
	s_addc_u32 s9, s9, s55
	v_cmp_gt_i64_e32 vcc, s[8:9], v[136:137]
	s_mov_b64 s[12:13], -1
	s_cbranch_vccnz .Lfrup_issued
	s_ashr_i32 s4, s8, 31
	s_lshr_b32 s4, s4, 29
	s_add_i32 s4, s8, s4
	s_ashr_i32 s5, s4, 3
	s_and_b32 s4, s4, -8
	s_sub_i32 s4, s8, s4
	s_cmp_lt_i32 s4, 0
	s_cselect_b32 s12, s43, 0x160
	s_mul_i32 s4, s4, s12
	s_add_i32 s4, s4, s5
	s_mul_hi_i32 s5, s4, 0x2e8ba2e9
	s_lshr_b32 s12, s5, 31
	s_ashr_i32 s5, s5, 4
	s_add_i32 s5, s5, s12
	s_mul_i32 s12, s5, 0x58
	s_lshl_b32 s5, s5, 2
	s_sub_i32 s4, s4, s12
	s_sub_i32 s12, 0x80, s5
	s_min_i32 s12, s12, 4
	s_abs_i32 s12, s12
	v_cvt_f32_u32_e32 v6, s12
	s_sub_i32 s19, 0, s12
	s_ashr_i32 s13, s4, 31
	s_abs_i32 s4, s4
	v_rcp_iflag_f32_e32 v6, v6
	s_nop 0
	v_mul_f32_e32 v6, 0x4f7ffffe, v6
	v_cvt_u32_f32_e32 v6, v6
	s_nop 0
	v_readfirstlane_b32 s21, v6
	s_mul_i32 s19, s19, s21
	s_mul_hi_u32 s19, s21, s19
	s_add_i32 s21, s21, s19
	s_mul_hi_u32 s19, s4, s21
	s_mul_i32 s19, s19, s12
	s_sub_i32 s4, s4, s19
	s_sub_i32 s19, s4, s12
	s_cmp_ge_u32 s4, s12
	s_cselect_b32 s4, s19, s4
	s_sub_i32 s19, s4, s12
	s_cmp_ge_u32 s4, s12
	s_cselect_b32 s4, s19, s4
	s_xor_b32 s4, s4, s13
	s_sub_i32 s4, s4, s13
	s_add_i32 s5, s5, s4
	v_lshl_add_u32 v6, s5, 8, v4
	s_waitcnt lgkmcnt(0)
	v_ashrrev_i32_e32 v7, 31, v6
	v_lshlrev_b64 v[6:7], 6, v[6:7]
	v_lshl_add_u64 v[10:11], v[2:3], 0, v[6:7]
	global_load_dwordx4 v[70:73], v[10:11], off
	global_load_dwordx4 v[74:77], v[10:11], off offset:16
	s_add_u32 s8, s8, s14
	s_addc_u32 s9, s9, s55
	v_cmp_gt_i64_e32 vcc, s[8:9], v[136:137]
	s_mov_b64 s[12:13], -1
	s_cbranch_vccnz .Lfrup_issued
	s_ashr_i32 s4, s8, 31
	s_lshr_b32 s4, s4, 29
	s_add_i32 s4, s8, s4
	s_ashr_i32 s5, s4, 3
	s_and_b32 s4, s4, -8
	s_sub_i32 s4, s8, s4
	s_cmp_lt_i32 s4, 0
	s_cselect_b32 s12, s43, 0x160
	s_mul_i32 s4, s4, s12
	s_add_i32 s4, s4, s5
	s_mul_hi_i32 s5, s4, 0x2e8ba2e9
	s_lshr_b32 s12, s5, 31
	s_ashr_i32 s5, s5, 4
	s_add_i32 s5, s5, s12
	s_mul_i32 s12, s5, 0x58
	s_lshl_b32 s5, s5, 2
	s_sub_i32 s4, s4, s12
	s_sub_i32 s12, 0x80, s5
	s_min_i32 s12, s12, 4
	s_abs_i32 s12, s12
	v_cvt_f32_u32_e32 v6, s12
	s_sub_i32 s19, 0, s12
	s_ashr_i32 s13, s4, 31
	s_abs_i32 s4, s4
	v_rcp_iflag_f32_e32 v6, v6
	s_nop 0
	v_mul_f32_e32 v6, 0x4f7ffffe, v6
	v_cvt_u32_f32_e32 v6, v6
	s_nop 0
	v_readfirstlane_b32 s21, v6
	s_mul_i32 s19, s19, s21
	s_mul_hi_u32 s19, s21, s19
	s_add_i32 s21, s21, s19
	s_mul_hi_u32 s19, s4, s21
	s_mul_i32 s19, s19, s12
	s_sub_i32 s4, s4, s19
	s_sub_i32 s19, s4, s12
	s_cmp_ge_u32 s4, s12
	s_cselect_b32 s4, s19, s4
	s_sub_i32 s19, s4, s12
	s_cmp_ge_u32 s4, s12
	s_cselect_b32 s4, s19, s4
	s_xor_b32 s4, s4, s13
	s_sub_i32 s4, s4, s13
	s_add_i32 s5, s5, s4
	v_lshl_add_u32 v6, s5, 8, v4
	s_waitcnt lgkmcnt(0)
	v_ashrrev_i32_e32 v7, 31, v6
	v_lshlrev_b64 v[6:7], 6, v[6:7]
	v_lshl_add_u64 v[10:11], v[2:3], 0, v[6:7]
	global_load_dwordx4 v[78:81], v[10:11], off
	global_load_dwordx4 v[82:85], v[10:11], off offset:16
	s_add_u32 s8, s8, s14
	s_addc_u32 s9, s9, s55
	v_cmp_gt_i64_e32 vcc, s[8:9], v[136:137]
	s_mov_b64 s[12:13], -1
	s_cbranch_vccnz .Lfrup_issued
	s_ashr_i32 s4, s8, 31
	s_lshr_b32 s4, s4, 29
	s_add_i32 s4, s8, s4
	s_ashr_i32 s5, s4, 3
	s_and_b32 s4, s4, -8
	s_sub_i32 s4, s8, s4
	s_cmp_lt_i32 s4, 0
	s_cselect_b32 s12, s43, 0x160
	s_mul_i32 s4, s4, s12
	s_add_i32 s4, s4, s5
	s_mul_hi_i32 s5, s4, 0x2e8ba2e9
	s_lshr_b32 s12, s5, 31
	s_ashr_i32 s5, s5, 4
	s_add_i32 s5, s5, s12
	s_mul_i32 s12, s5, 0x58
	s_lshl_b32 s5, s5, 2
	s_sub_i32 s4, s4, s12
	s_sub_i32 s12, 0x80, s5
	s_min_i32 s12, s12, 4
	s_abs_i32 s12, s12
	v_cvt_f32_u32_e32 v6, s12
	s_sub_i32 s19, 0, s12
	s_ashr_i32 s13, s4, 31
	s_abs_i32 s4, s4
	v_rcp_iflag_f32_e32 v6, v6
	s_nop 0
	v_mul_f32_e32 v6, 0x4f7ffffe, v6
	v_cvt_u32_f32_e32 v6, v6
	s_nop 0
	v_readfirstlane_b32 s21, v6
	s_mul_i32 s19, s19, s21
	s_mul_hi_u32 s19, s21, s19
	s_add_i32 s21, s21, s19
	s_mul_hi_u32 s19, s4, s21
	s_mul_i32 s19, s19, s12
	s_sub_i32 s4, s4, s19
	s_sub_i32 s19, s4, s12
	s_cmp_ge_u32 s4, s12
	s_cselect_b32 s4, s19, s4
	s_sub_i32 s19, s4, s12
	s_cmp_ge_u32 s4, s12
	s_cselect_b32 s4, s19, s4
	s_xor_b32 s4, s4, s13
	s_sub_i32 s4, s4, s13
	s_add_i32 s5, s5, s4
	v_lshl_add_u32 v6, s5, 8, v4
	s_waitcnt lgkmcnt(0)
	v_ashrrev_i32_e32 v7, 31, v6
	v_lshlrev_b64 v[6:7], 6, v[6:7]
	v_lshl_add_u64 v[10:11], v[2:3], 0, v[6:7]
	global_load_dwordx4 v[86:89], v[10:11], off
	global_load_dwordx4 v[90:93], v[10:11], off offset:16
	s_add_u32 s8, s8, s14
	s_addc_u32 s9, s9, s55
	v_cmp_gt_i64_e32 vcc, s[8:9], v[136:137]
	s_mov_b64 s[12:13], -1
	s_cbranch_vccnz .Lfrup_issued
	s_ashr_i32 s4, s8, 31
	s_lshr_b32 s4, s4, 29
	s_add_i32 s4, s8, s4
	s_ashr_i32 s5, s4, 3
	s_and_b32 s4, s4, -8
	s_sub_i32 s4, s8, s4
	s_cmp_lt_i32 s4, 0
	s_cselect_b32 s12, s43, 0x160
	s_mul_i32 s4, s4, s12
	s_add_i32 s4, s4, s5
	s_mul_hi_i32 s5, s4, 0x2e8ba2e9
	s_lshr_b32 s12, s5, 31
	s_ashr_i32 s5, s5, 4
	s_add_i32 s5, s5, s12
	s_mul_i32 s12, s5, 0x58
	s_lshl_b32 s5, s5, 2
	s_sub_i32 s4, s4, s12
	s_sub_i32 s12, 0x80, s5
	s_min_i32 s12, s12, 4
	s_abs_i32 s12, s12
	v_cvt_f32_u32_e32 v6, s12
	s_sub_i32 s19, 0, s12
	s_ashr_i32 s13, s4, 31
	s_abs_i32 s4, s4
	v_rcp_iflag_f32_e32 v6, v6
	s_nop 0
	v_mul_f32_e32 v6, 0x4f7ffffe, v6
	v_cvt_u32_f32_e32 v6, v6
	s_nop 0
	v_readfirstlane_b32 s21, v6
	s_mul_i32 s19, s19, s21
	s_mul_hi_u32 s19, s21, s19
	s_add_i32 s21, s21, s19
	s_mul_hi_u32 s19, s4, s21
	s_mul_i32 s19, s19, s12
	s_sub_i32 s4, s4, s19
	s_sub_i32 s19, s4, s12
	s_cmp_ge_u32 s4, s12
	s_cselect_b32 s4, s19, s4
	s_sub_i32 s19, s4, s12
	s_cmp_ge_u32 s4, s12
	s_cselect_b32 s4, s19, s4
	s_xor_b32 s4, s4, s13
	s_sub_i32 s4, s4, s13
	s_add_i32 s5, s5, s4
	v_lshl_add_u32 v6, s5, 8, v4
	s_waitcnt lgkmcnt(0)
	v_ashrrev_i32_e32 v7, 31, v6
	v_lshlrev_b64 v[6:7], 6, v[6:7]
	v_lshl_add_u64 v[10:11], v[2:3], 0, v[6:7]
	global_load_dwordx4 v[94:97], v[10:11], off
	global_load_dwordx4 v[98:101], v[10:11], off offset:16
	s_add_u32 s8, s8, s14
	s_addc_u32 s9, s9, s55
.Lfrup_issued:
	s_waitcnt vmcnt(0)
	s_mov_b64 s[8:9], s[2:3]
	v_cmp_gt_i64_e32 vcc, s[8:9], v[136:137]
	s_mov_b64 s[12:13], -1
	s_cbranch_vccnz .Lfrup_done
	v_pk_add_f32 v[16:17], v[16:17], v[20:21]
	v_pk_add_f32 v[14:15], v[14:15], v[18:19]
	v_cmp_lt_i32_e32 vcc, v172, v171
	v_add_f32_e32 v6, v14, v15
	v_add_f32_e32 v7, v16, v17
	v_add_f32_e32 v6, v6, v7
	v_cndmask_b32_e32 v7, v170, v172, vcc
	v_lshlrev_b32_e32 v7, 2, v7
	ds_bpermute_b32 v7, v7, v6
	s_and_saveexec_b64 s[12:13], s[6:7]
	s_waitcnt lgkmcnt(0)
	v_add_f32_e32 v6, v6, v7
	v_fmamk_f32 v6, v6, 0x3a800000, v166
	v_rsq_f32_e32 v6, v6
	ds_write_b32 v5, v6
	s_or_b64 exec, exec, s[12:13]
	s_add_u32 s8, s8, s14
	s_addc_u32 s9, s9, s55
	v_cmp_gt_i64_e32 vcc, s[8:9], v[136:137]
	s_mov_b64 s[12:13], -1
	s_cbranch_vccnz .Lfrup_done
	v_pk_add_f32 v[24:25], v[24:25], v[28:29]
	v_pk_add_f32 v[22:23], v[22:23], v[26:27]
	v_cmp_lt_i32_e32 vcc, v172, v171
	v_add_f32_e32 v6, v22, v23
	v_add_f32_e32 v7, v24, v25
	v_add_f32_e32 v6, v6, v7
	v_cndmask_b32_e32 v7, v170, v172, vcc
	v_lshlrev_b32_e32 v7, 2, v7
	ds_bpermute_b32 v7, v7, v6
	s_and_saveexec_b64 s[12:13], s[6:7]
	s_waitcnt lgkmcnt(0)
	v_add_f32_e32 v6, v6, v7
	v_fmamk_f32 v6, v6, 0x3a800000, v166
	v_rsq_f32_e32 v6, v6
	ds_write_b32 v5, v6 offset:1024
	s_or_b64 exec, exec, s[12:13]
	s_add_u32 s8, s8, s14
	s_addc_u32 s9, s9, s55
	v_cmp_gt_i64_e32 vcc, s[8:9], v[136:137]
	s_mov_b64 s[12:13], -1
	s_cbranch_vccnz .Lfrup_done
	v_pk_add_f32 v[32:33], v[32:33], v[36:37]
	v_pk_add_f32 v[30:31], v[30:31], v[34:35]
	v_cmp_lt_i32_e32 vcc, v172, v171
	v_add_f32_e32 v6, v30, v31
	v_add_f32_e32 v7, v32, v33
	v_add_f32_e32 v6, v6, v7
	v_cndmask_b32_e32 v7, v170, v172, vcc
	v_lshlrev_b32_e32 v7, 2, v7
	ds_bpermute_b32 v7, v7, v6
	s_and_saveexec_b64 s[12:13], s[6:7]
	s_waitcnt lgkmcnt(0)
	v_add_f32_e32 v6, v6, v7
	v_fmamk_f32 v6, v6, 0x3a800000, v166
	v_rsq_f32_e32 v6, v6
	ds_write_b32 v5, v6 offset:2048
	s_or_b64 exec, exec, s[12:13]
	s_add_u32 s8, s8, s14
	s_addc_u32 s9, s9, s55
	v_cmp_gt_i64_e32 vcc, s[8:9], v[136:137]
	s_mov_b64 s[12:13], -1
	s_cbranch_vccnz .Lfrup_done
	v_pk_add_f32 v[40:41], v[40:41], v[44:45]
	v_pk_add_f32 v[38:39], v[38:39], v[42:43]
	v_cmp_lt_i32_e32 vcc, v172, v171
	v_add_f32_e32 v6, v38, v39
	v_add_f32_e32 v7, v40, v41
	v_add_f32_e32 v6, v6, v7
	v_cndmask_b32_e32 v7, v170, v172, vcc
	v_lshlrev_b32_e32 v7, 2, v7
	ds_bpermute_b32 v7, v7, v6
	s_and_saveexec_b64 s[12:13], s[6:7]
	s_waitcnt lgkmcnt(0)
	v_add_f32_e32 v6, v6, v7
	v_fmamk_f32 v6, v6, 0x3a800000, v166
	v_rsq_f32_e32 v6, v6
	ds_write_b32 v5, v6 offset:3072
	s_or_b64 exec, exec, s[12:13]
	s_add_u32 s8, s8, s14
	s_addc_u32 s9, s9, s55
	v_cmp_gt_i64_e32 vcc, s[8:9], v[136:137]
	s_mov_b64 s[12:13], -1
	s_cbranch_vccnz .Lfrup_done
	v_pk_add_f32 v[48:49], v[48:49], v[52:53]
	v_pk_add_f32 v[46:47], v[46:47], v[50:51]
	v_cmp_lt_i32_e32 vcc, v172, v171
	v_add_f32_e32 v6, v46, v47
	v_add_f32_e32 v7, v48, v49
	v_add_f32_e32 v6, v6, v7
	v_cndmask_b32_e32 v7, v170, v172, vcc
	v_lshlrev_b32_e32 v7, 2, v7
	ds_bpermute_b32 v7, v7, v6
	s_and_saveexec_b64 s[12:13], s[6:7]
	s_waitcnt lgkmcnt(0)
	v_add_f32_e32 v6, v6, v7
	v_fmamk_f32 v6, v6, 0x3a800000, v166
	v_rsq_f32_e32 v6, v6
	ds_write_b32 v5, v6 offset:4096
	s_or_b64 exec, exec, s[12:13]
	s_add_u32 s8, s8, s14
	s_addc_u32 s9, s9, s55
	v_cmp_gt_i64_e32 vcc, s[8:9], v[136:137]
	s_mov_b64 s[12:13], -1
	s_cbranch_vccnz .Lfrup_done
	v_pk_add_f32 v[56:57], v[56:57], v[60:61]
	v_pk_add_f32 v[54:55], v[54:55], v[58:59]
	v_cmp_lt_i32_e32 vcc, v172, v171
	v_add_f32_e32 v6, v54, v55
	v_add_f32_e32 v7, v56, v57
	v_add_f32_e32 v6, v6, v7
	v_cndmask_b32_e32 v7, v170, v172, vcc
	v_lshlrev_b32_e32 v7, 2, v7
	ds_bpermute_b32 v7, v7, v6
	s_and_saveexec_b64 s[12:13], s[6:7]
	s_waitcnt lgkmcnt(0)
	v_add_f32_e32 v6, v6, v7
	v_fmamk_f32 v6, v6, 0x3a800000, v166
	v_rsq_f32_e32 v6, v6
	ds_write_b32 v5, v6 offset:5120
	s_or_b64 exec, exec, s[12:13]
	s_add_u32 s8, s8, s14
	s_addc_u32 s9, s9, s55
	v_cmp_gt_i64_e32 vcc, s[8:9], v[136:137]
	s_mov_b64 s[12:13], -1
	s_cbranch_vccnz .Lfrup_done
	v_pk_add_f32 v[64:65], v[64:65], v[68:69]
	v_pk_add_f32 v[62:63], v[62:63], v[66:67]
	v_cmp_lt_i32_e32 vcc, v172, v171
	v_add_f32_e32 v6, v62, v63
	v_add_f32_e32 v7, v64, v65
	v_add_f32_e32 v6, v6, v7
	v_cndmask_b32_e32 v7, v170, v172, vcc
	v_lshlrev_b32_e32 v7, 2, v7
	ds_bpermute_b32 v7, v7, v6
	s_and_saveexec_b64 s[12:13], s[6:7]
	s_waitcnt lgkmcnt(0)
	v_add_f32_e32 v6, v6, v7
	v_fmamk_f32 v6, v6, 0x3a800000, v166
	v_rsq_f32_e32 v6, v6
	ds_write_b32 v5, v6 offset:6144
	s_or_b64 exec, exec, s[12:13]
	s_add_u32 s8, s8, s14
	s_addc_u32 s9, s9, s55
	v_cmp_gt_i64_e32 vcc, s[8:9], v[136:137]
	s_mov_b64 s[12:13], -1
	s_cbranch_vccnz .Lfrup_done
	v_pk_add_f32 v[72:73], v[72:73], v[76:77]
	v_pk_add_f32 v[70:71], v[70:71], v[74:75]
	v_cmp_lt_i32_e32 vcc, v172, v171
	v_add_f32_e32 v6, v70, v71
	v_add_f32_e32 v7, v72, v73
	v_add_f32_e32 v6, v6, v7
	v_cndmask_b32_e32 v7, v170, v172, vcc
	v_lshlrev_b32_e32 v7, 2, v7
	ds_bpermute_b32 v7, v7, v6
	s_and_saveexec_b64 s[12:13], s[6:7]
	s_waitcnt lgkmcnt(0)
	v_add_f32_e32 v6, v6, v7
	v_fmamk_f32 v6, v6, 0x3a800000, v166
	v_rsq_f32_e32 v6, v6
	ds_write_b32 v5, v6 offset:7168
	s_or_b64 exec, exec, s[12:13]
	s_add_u32 s8, s8, s14
	s_addc_u32 s9, s9, s55
	v_cmp_gt_i64_e32 vcc, s[8:9], v[136:137]
	s_mov_b64 s[12:13], -1
	s_cbranch_vccnz .Lfrup_done
	v_pk_add_f32 v[80:81], v[80:81], v[84:85]
	v_pk_add_f32 v[78:79], v[78:79], v[82:83]
	v_cmp_lt_i32_e32 vcc, v172, v171
	v_add_f32_e32 v6, v78, v79
	v_add_f32_e32 v7, v80, v81
	v_add_f32_e32 v6, v6, v7
	v_cndmask_b32_e32 v7, v170, v172, vcc
	v_lshlrev_b32_e32 v7, 2, v7
	ds_bpermute_b32 v7, v7, v6
	s_and_saveexec_b64 s[12:13], s[6:7]
	s_waitcnt lgkmcnt(0)
	v_add_f32_e32 v6, v6, v7
	v_fmamk_f32 v6, v6, 0x3a800000, v166
	v_rsq_f32_e32 v6, v6
	ds_write_b32 v5, v6 offset:8192
	s_or_b64 exec, exec, s[12:13]
	s_add_u32 s8, s8, s14
	s_addc_u32 s9, s9, s55
	v_cmp_gt_i64_e32 vcc, s[8:9], v[136:137]
	s_mov_b64 s[12:13], -1
	s_cbranch_vccnz .Lfrup_done
	v_pk_add_f32 v[88:89], v[88:89], v[92:93]
	v_pk_add_f32 v[86:87], v[86:87], v[90:91]
	v_cmp_lt_i32_e32 vcc, v172, v171
	v_add_f32_e32 v6, v86, v87
	v_add_f32_e32 v7, v88, v89
	v_add_f32_e32 v6, v6, v7
	v_cndmask_b32_e32 v7, v170, v172, vcc
	v_lshlrev_b32_e32 v7, 2, v7
	ds_bpermute_b32 v7, v7, v6
	s_and_saveexec_b64 s[12:13], s[6:7]
	s_waitcnt lgkmcnt(0)
	v_add_f32_e32 v6, v6, v7
	v_fmamk_f32 v6, v6, 0x3a800000, v166
	v_rsq_f32_e32 v6, v6
	ds_write_b32 v5, v6 offset:9216
	s_or_b64 exec, exec, s[12:13]
	s_add_u32 s8, s8, s14
	s_addc_u32 s9, s9, s55
	v_cmp_gt_i64_e32 vcc, s[8:9], v[136:137]
	s_mov_b64 s[12:13], -1
	s_cbranch_vccnz .Lfrup_done
	v_pk_add_f32 v[96:97], v[96:97], v[100:101]
	v_pk_add_f32 v[94:95], v[94:95], v[98:99]
	v_cmp_lt_i32_e32 vcc, v172, v171
	v_add_f32_e32 v6, v94, v95
	v_add_f32_e32 v7, v96, v97
	v_add_f32_e32 v6, v6, v7
	v_cndmask_b32_e32 v7, v170, v172, vcc
	v_lshlrev_b32_e32 v7, 2, v7
	ds_bpermute_b32 v7, v7, v6
	s_and_saveexec_b64 s[12:13], s[6:7]
	s_waitcnt lgkmcnt(0)
	v_add_f32_e32 v6, v6, v7
	v_fmamk_f32 v6, v6, 0x3a800000, v166
	v_rsq_f32_e32 v6, v6
	ds_write_b32 v5, v6 offset:10240
	s_or_b64 exec, exec, s[12:13]
	s_add_u32 s8, s8, s14
	s_addc_u32 s9, s9, s55
.Lfrup_done:
.LBB0_274:
	v_readlane_b32 s4, v254, 11
	v_readlane_b32 s5, v254, 12
	s_andn2_b64 vcc, exec, s[4:5]
	v_readfirstlane_b32 s6, v130
	s_waitcnt vmcnt(0) lgkmcnt(0)
	s_barrier
	s_cbranch_vccnz .LBB0_290
	v_lshlrev_b32_e32 v2, 4, v130
	v_add_u32_e32 v3, 0x2000, v2
	v_ashrrev_i32_e32 v4, 31, v3
	v_lshrrev_b32_e32 v4, 22, v4
	v_add_u32_e32 v4, v3, v4
	v_ashrrev_i32_e32 v10, 10, v4
	v_mul_i32_i24_e32 v4, 0x400, v10
	v_sub_u32_e32 v3, v3, v4
	v_lshrrev_b32_e32 v4, 4, v3
	v_bitop3_b32 v3, v4, v3, 32 bitop3:0x6c
	v_ashrrev_i32_e32 v4, 31, v3
	v_lshrrev_b32_e32 v4, 26, v4
	v_add_u32_e32 v4, v3, v4
	v_lshlrev_b32_e32 v5, 3, v10
	v_ashrrev_i32_e32 v11, 6, v4
	v_and_b32_e32 v5, -16, v5
	v_add_u32_e32 v5, v11, v5
	v_and_b32_e32 v6, 3, v11
	s_mov_b32 s8, 0x1fffe0
	v_lshrrev_b32_e32 v7, 2, v5
	v_lshlrev_b32_e32 v8, 1, v5
	v_and_b32_e32 v4, 0xc0, v4
	v_and_or_b32 v6, v5, s8, v6
	v_and_b32_e32 v7, 4, v7
	v_and_b32_e32 v8, 24, v8
	v_sub_u32_e32 v3, v3, v4
	v_or3_b32 v6, v6, v7, v8
	v_lshlrev_b32_e32 v7, 5, v10
	v_ashrrev_i16_sdwa v3, v169, sext(v3) dst_sel:DWORD dst_unused:UNUSED_PAD src0_sel:DWORD src1_sel:BYTE_0
	v_and_b32_e32 v7, 32, v7
	v_bfe_i32 v12, v3, 0, 16
	v_add_lshl_u32 v3, v7, v12, 1
	v_lshl_add_u32 v132, v6, 11, v3
	v_lshl_add_u32 v144, v5, 11, v3
	v_bfe_i32 v3, v130, 27, 1
	v_lshrrev_b32_e32 v3, 22, v3
	v_add_u32_e32 v3, v2, v3
	v_and_b32_e32 v3, 0xfffffc00, v3
	v_sub_u32_e32 v2, v2, v3
	v_lshrrev_b32_e32 v3, 4, v2
	v_ashrrev_i32_e32 v4, 31, v130
	v_bitop3_b32 v2, v3, v2, 32 bitop3:0x6c
	v_lshrrev_b32_e32 v4, 26, v4
	v_ashrrev_i32_e32 v3, 31, v2
	v_add_u32_e32 v4, v130, v4
	v_lshrrev_b32_e32 v3, 26, v3
	v_ashrrev_i32_e32 v14, 6, v4
	s_mul_i32 s4, s35, 0xb00000
	v_add_u32_e32 v3, v2, v3
	v_lshlrev_b32_e32 v4, 3, v14
	s_add_u32 s4, s82, s4
	v_ashrrev_i32_e32 v13, 6, v3
	v_and_b32_e32 v4, -16, v4
	s_addc_u32 s5, s83, 0
	v_add_u32_e32 v4, v13, v4
	s_add_u32 s4, s4, 0x2000000
	v_and_b32_e32 v5, 3, v13
	v_lshrrev_b32_e32 v6, 2, v4
	v_lshlrev_b32_e32 v7, 1, v4
	v_and_b32_e32 v3, 0xc0, v3
	s_addc_u32 s5, s5, 0
	s_ashr_i32 s12, s6, 6
	v_and_or_b32 v5, v4, s8, v5
	v_and_b32_e32 v6, 4, v6
	v_and_b32_e32 v7, 24, v7
	v_sub_u32_e32 v2, v2, v3
	s_mov_b32 s41, s31
	s_ashr_i32 s7, s6, 8
	s_lshl_b32 s31, s12, 10
	v_or3_b32 v5, v5, v6, v7
	v_lshlrev_b32_e32 v6, 5, v14
	v_ashrrev_i16_sdwa v2, v169, sext(v2) dst_sel:DWORD dst_unused:UNUSED_PAD src0_sel:DWORD src1_sel:BYTE_0
	v_readlane_b32 s8, v254, 25
	v_and_b32_e32 v6, 32, v6
	v_bfe_i32 v15, v2, 0, 16
	v_readlane_b32 s9, v254, 26
	s_add_u32 s26, s4, s8
	v_add_lshl_u32 v2, v6, v15, 1
	s_addc_u32 s27, s5, s9
	s_add_i32 s50, s31, 0
	v_lshl_add_u32 v134, v5, 11, v2
	s_add_i32 m0, s50, 0x10000
	v_lshl_add_u32 v146, v4, 11, v2
	global_load_lds_dwordx4 v134, s[26:27]
	s_add_i32 m0, s50, 0x12000
	s_add_u32 s8, s26, 0x40000
	global_load_lds_dwordx4 v132, s[26:27]
	s_addc_u32 s9, s27, 0
	s_add_i32 m0, s50, 0x14000
	v_mov_b32_e32 v133, v135
	global_load_lds_dwordx4 v134, s[8:9]
	s_add_i32 m0, s50, 0x16000
	v_mov_b32_e32 v147, v135
	global_load_lds_dwordx4 v132, s[8:9]
	v_readlane_b32 s8, v254, 23
	v_readlane_b32 s9, v254, 24
	s_add_u32 s22, s78, s8
	s_addc_u32 s23, s79, s9
	s_add_i32 s51, s50, 0x2000
	s_mov_b32 m0, s50
	s_add_u32 s8, s22, 0x40000
	global_load_lds_dwordx4 v146, s[22:23]
	s_mov_b32 m0, s51
	s_addc_u32 s9, s23, 0
	s_add_i32 s52, s50, 0x4000
	global_load_lds_dwordx4 v144, s[22:23]
	s_mov_b32 m0, s52
	s_add_i32 s53, s50, 0x6000
	global_load_lds_dwordx4 v146, s[8:9]
	s_mov_b32 m0, s53
	v_mov_b32_e32 v145, v135
	global_load_lds_dwordx4 v144, s[8:9]
	s_cmp_eq_u32 s7, 1
	v_lshl_add_u64 v[8:9], s[26:27], 0, v[134:135]
	v_lshl_add_u64 v[6:7], s[26:27], 0, v[132:133]
	v_lshl_add_u64 v[2:3], s[22:23], 0, v[146:147]
	s_cselect_b64 s[8:9], -1, 0
	s_cmp_lg_u32 s7, 1
	v_lshl_add_u64 v[4:5], s[22:23], 0, v[144:145]
	s_cbranch_scc1 .LBB0_277
	s_barrier

.LBB0_397:
	s_nop 0
	v_and_b32_e32 v5, 1, v130
	v_ashrrev_i32_e32 v4, 1, v130
	v_lshlrev_b32_e32 v134, 5, v5
	v_readlane_b32 s4, v255, 0
	s_waitcnt lgkmcnt(0)
	v_lshl_add_u64 v[2:3], s[82:83], 0, v[134:135]
	v_cmp_eq_u32_e64 s[6:7], 0, v5
	v_lshl_add_u32 v5, v4, 2, s4
	s_mov_b64 s[8:9], s[2:3]
	v_cmp_gt_i64_e32 vcc, s[8:9], v[140:141]
	s_mov_b64 s[10:11], -1
	s_cbranch_vccnz .Lfrain_issued
	s_ashr_i32 s4, s8, 31
	s_lshr_b32 s4, s4, 29
	s_add_i32 s4, s8, s4
	s_ashr_i32 s5, s4, 3
	s_and_b32 s4, s4, -8
	s_sub_i32 s4, s8, s4
	s_cmp_lt_i32 s4, 0
	s_cselect_b32 s10, s48, 0xa0
	s_mul_i32 s4, s4, s10
	s_add_i32 s4, s4, s5
	s_mul_hi_i32 s5, s4, 0x66666667
	s_lshr_b32 s10, s5, 31
	s_ashr_i32 s5, s5, 4
	s_add_i32 s5, s5, s10
	s_mul_i32 s10, s5, 40
	s_lshl_b32 s5, s5, 2
	s_sub_i32 s4, s4, s10
	s_sub_i32 s10, 0x80, s5
	s_min_i32 s10, s10, 4
	s_abs_i32 s10, s10
	v_cvt_f32_u32_e32 v6, s10
	s_sub_i32 s12, 0, s10
	s_ashr_i32 s11, s4, 31
	s_abs_i32 s4, s4
	v_rcp_iflag_f32_e32 v6, v6
	s_nop 0
	v_mul_f32_e32 v6, 0x4f7ffffe, v6
	v_cvt_u32_f32_e32 v6, v6
	s_nop 0
	v_readfirstlane_b32 s13, v6
	s_mul_i32 s12, s12, s13
	s_mul_hi_u32 s12, s13, s12
	s_add_i32 s13, s13, s12
	s_mul_hi_u32 s12, s4, s13
	s_mul_i32 s12, s12, s10
	s_sub_i32 s4, s4, s12
	s_sub_i32 s12, s4, s10
	s_cmp_ge_u32 s4, s10
	s_cselect_b32 s4, s12, s4
	s_sub_i32 s12, s4, s10
	s_cmp_ge_u32 s4, s10
	s_cselect_b32 s4, s12, s4
	s_xor_b32 s4, s4, s11
	s_sub_i32 s4, s4, s11
	s_add_i32 s5, s5, s4
	v_lshl_add_u32 v6, s5, 8, v4
	s_waitcnt lgkmcnt(0)
	v_ashrrev_i32_e32 v7, 31, v6
	v_lshlrev_b64 v[6:7], 6, v[6:7]
	v_lshl_add_u64 v[10:11], v[2:3], 0, v[6:7]
	global_load_dwordx4 v[14:17], v[10:11], off
	global_load_dwordx4 v[18:21], v[10:11], off offset:16
	s_add_u32 s8, s8, s14
	s_addc_u32 s9, s9, s55
	v_cmp_gt_i64_e32 vcc, s[8:9], v[140:141]
	s_mov_b64 s[10:11], -1
	s_cbranch_vccnz .Lfrain_issued
	s_ashr_i32 s4, s8, 31
	s_lshr_b32 s4, s4, 29
	s_add_i32 s4, s8, s4
	s_ashr_i32 s5, s4, 3
	s_and_b32 s4, s4, -8
	s_sub_i32 s4, s8, s4
	s_cmp_lt_i32 s4, 0
	s_cselect_b32 s10, s48, 0xa0
	s_mul_i32 s4, s4, s10
	s_add_i32 s4, s4, s5
	s_mul_hi_i32 s5, s4, 0x66666667
	s_lshr_b32 s10, s5, 31
	s_ashr_i32 s5, s5, 4
	s_add_i32 s5, s5, s10
	s_mul_i32 s10, s5, 40
	s_lshl_b32 s5, s5, 2
	s_sub_i32 s4, s4, s10
	s_sub_i32 s10, 0x80, s5
	s_min_i32 s10, s10, 4
	s_abs_i32 s10, s10
	v_cvt_f32_u32_e32 v6, s10
	s_sub_i32 s12, 0, s10
	s_ashr_i32 s11, s4, 31
	s_abs_i32 s4, s4
	v_rcp_iflag_f32_e32 v6, v6
	s_nop 0
	v_mul_f32_e32 v6, 0x4f7ffffe, v6
	v_cvt_u32_f32_e32 v6, v6
	s_nop 0
	v_readfirstlane_b32 s13, v6
	s_mul_i32 s12, s12, s13
	s_mul_hi_u32 s12, s13, s12
	s_add_i32 s13, s13, s12
	s_mul_hi_u32 s12, s4, s13
	s_mul_i32 s12, s12, s10
	s_sub_i32 s4, s4, s12
	s_sub_i32 s12, s4, s10
	s_cmp_ge_u32 s4, s10
	s_cselect_b32 s4, s12, s4
	s_sub_i32 s12, s4, s10
	s_cmp_ge_u32 s4, s10
	s_cselect_b32 s4, s12, s4
	s_xor_b32 s4, s4, s11
	s_sub_i32 s4, s4, s11
	s_add_i32 s5, s5, s4
	v_lshl_add_u32 v6, s5, 8, v4
	s_waitcnt lgkmcnt(0)
	v_ashrrev_i32_e32 v7, 31, v6
	v_lshlrev_b64 v[6:7], 6, v[6:7]
	v_lshl_add_u64 v[10:11], v[2:3], 0, v[6:7]
	global_load_dwordx4 v[22:25], v[10:11], off
	global_load_dwordx4 v[26:29], v[10:11], off offset:16
	s_add_u32 s8, s8, s14
	s_addc_u32 s9, s9, s55
	v_cmp_gt_i64_e32 vcc, s[8:9], v[140:141]
	s_mov_b64 s[10:11], -1
	s_cbranch_vccnz .Lfrain_issued
	s_ashr_i32 s4, s8, 31
	s_lshr_b32 s4, s4, 29
	s_add_i32 s4, s8, s4
	s_ashr_i32 s5, s4, 3
	s_and_b32 s4, s4, -8
	s_sub_i32 s4, s8, s4
	s_cmp_lt_i32 s4, 0
	s_cselect_b32 s10, s48, 0xa0
	s_mul_i32 s4, s4, s10
	s_add_i32 s4, s4, s5
	s_mul_hi_i32 s5, s4, 0x66666667
	s_lshr_b32 s10, s5, 31
	s_ashr_i32 s5, s5, 4
	s_add_i32 s5, s5, s10
	s_mul_i32 s10, s5, 40
	s_lshl_b32 s5, s5, 2
	s_sub_i32 s4, s4, s10
	s_sub_i32 s10, 0x80, s5
	s_min_i32 s10, s10, 4
	s_abs_i32 s10, s10
	v_cvt_f32_u32_e32 v6, s10
	s_sub_i32 s12, 0, s10
	s_ashr_i32 s11, s4, 31
	s_abs_i32 s4, s4
	v_rcp_iflag_f32_e32 v6, v6
	s_nop 0
	v_mul_f32_e32 v6, 0x4f7ffffe, v6
	v_cvt_u32_f32_e32 v6, v6
	s_nop 0
	v_readfirstlane_b32 s13, v6
	s_mul_i32 s12, s12, s13
	s_mul_hi_u32 s12, s13, s12
	s_add_i32 s13, s13, s12
	s_mul_hi_u32 s12, s4, s13
	s_mul_i32 s12, s12, s10
	s_sub_i32 s4, s4, s12
	s_sub_i32 s12, s4, s10
	s_cmp_ge_u32 s4, s10
	s_cselect_b32 s4, s12, s4
	s_sub_i32 s12, s4, s10
	s_cmp_ge_u32 s4, s10
	s_cselect_b32 s4, s12, s4
	s_xor_b32 s4, s4, s11
	s_sub_i32 s4, s4, s11
	s_add_i32 s5, s5, s4
	v_lshl_add_u32 v6, s5, 8, v4
	s_waitcnt lgkmcnt(0)
	v_ashrrev_i32_e32 v7, 31, v6
	v_lshlrev_b64 v[6:7], 6, v[6:7]
	v_lshl_add_u64 v[10:11], v[2:3], 0, v[6:7]
	global_load_dwordx4 v[30:33], v[10:11], off
	global_load_dwordx4 v[34:37], v[10:11], off offset:16
	s_add_u32 s8, s8, s14
	s_addc_u32 s9, s9, s55
	v_cmp_gt_i64_e32 vcc, s[8:9], v[140:141]
	s_mov_b64 s[10:11], -1
	s_cbranch_vccnz .Lfrain_issued
	s_ashr_i32 s4, s8, 31
	s_lshr_b32 s4, s4, 29
	s_add_i32 s4, s8, s4
	s_ashr_i32 s5, s4, 3
	s_and_b32 s4, s4, -8
	s_sub_i32 s4, s8, s4
	s_cmp_lt_i32 s4, 0
	s_cselect_b32 s10, s48, 0xa0
	s_mul_i32 s4, s4, s10
	s_add_i32 s4, s4, s5
	s_mul_hi_i32 s5, s4, 0x66666667
	s_lshr_b32 s10, s5, 31
	s_ashr_i32 s5, s5, 4
	s_add_i32 s5, s5, s10
	s_mul_i32 s10, s5, 40
	s_lshl_b32 s5, s5, 2
	s_sub_i32 s4, s4, s10
	s_sub_i32 s10, 0x80, s5
	s_min_i32 s10, s10, 4
	s_abs_i32 s10, s10
	v_cvt_f32_u32_e32 v6, s10
	s_sub_i32 s12, 0, s10
	s_ashr_i32 s11, s4, 31
	s_abs_i32 s4, s4
	v_rcp_iflag_f32_e32 v6, v6
	s_nop 0
	v_mul_f32_e32 v6, 0x4f7ffffe, v6
	v_cvt_u32_f32_e32 v6, v6
	s_nop 0
	v_readfirstlane_b32 s13, v6
	s_mul_i32 s12, s12, s13
	s_mul_hi_u32 s12, s13, s12
	s_add_i32 s13, s13, s12
	s_mul_hi_u32 s12, s4, s13
	s_mul_i32 s12, s12, s10
	s_sub_i32 s4, s4, s12
	s_sub_i32 s12, s4, s10
	s_cmp_ge_u32 s4, s10
	s_cselect_b32 s4, s12, s4
	s_sub_i32 s12, s4, s10
	s_cmp_ge_u32 s4, s10
	s_cselect_b32 s4, s12, s4
	s_xor_b32 s4, s4, s11
	s_sub_i32 s4, s4, s11
	s_add_i32 s5, s5, s4
	v_lshl_add_u32 v6, s5, 8, v4
	s_waitcnt lgkmcnt(0)
	v_ashrrev_i32_e32 v7, 31, v6
	v_lshlrev_b64 v[6:7], 6, v[6:7]
	v_lshl_add_u64 v[10:11], v[2:3], 0, v[6:7]
	global_load_dwordx4 v[38:41], v[10:11], off
	global_load_dwordx4 v[42:45], v[10:11], off offset:16
	s_add_u32 s8, s8, s14
	s_addc_u32 s9, s9, s55
	v_cmp_gt_i64_e32 vcc, s[8:9], v[140:141]
	s_mov_b64 s[10:11], -1
	s_cbranch_vccnz .Lfrain_issued
	s_ashr_i32 s4, s8, 31
	s_lshr_b32 s4, s4, 29
	s_add_i32 s4, s8, s4
	s_ashr_i32 s5, s4, 3
	s_and_b32 s4, s4, -8
	s_sub_i32 s4, s8, s4
	s_cmp_lt_i32 s4, 0
	s_cselect_b32 s10, s48, 0xa0
	s_mul_i32 s4, s4, s10
	s_add_i32 s4, s4, s5
	s_mul_hi_i32 s5, s4, 0x66666667
	s_lshr_b32 s10, s5, 31
	s_ashr_i32 s5, s5, 4
	s_add_i32 s5, s5, s10
	s_mul_i32 s10, s5, 40
	s_lshl_b32 s5, s5, 2
	s_sub_i32 s4, s4, s10
	s_sub_i32 s10, 0x80, s5
	s_min_i32 s10, s10, 4
	s_abs_i32 s10, s10
	v_cvt_f32_u32_e32 v6, s10
	s_sub_i32 s12, 0, s10
	s_ashr_i32 s11, s4, 31
	s_abs_i32 s4, s4
	v_rcp_iflag_f32_e32 v6, v6
	s_nop 0
	v_mul_f32_e32 v6, 0x4f7ffffe, v6
	v_cvt_u32_f32_e32 v6, v6
	s_nop 0
	v_readfirstlane_b32 s13, v6
	s_mul_i32 s12, s12, s13
	s_mul_hi_u32 s12, s13, s12
	s_add_i32 s13, s13, s12
	s_mul_hi_u32 s12, s4, s13
	s_mul_i32 s12, s12, s10
	s_sub_i32 s4, s4, s12
	s_sub_i32 s12, s4, s10
	s_cmp_ge_u32 s4, s10
	s_cselect_b32 s4, s12, s4
	s_sub_i32 s12, s4, s10
	s_cmp_ge_u32 s4, s10
	s_cselect_b32 s4, s12, s4
	s_xor_b32 s4, s4, s11
	s_sub_i32 s4, s4, s11
	s_add_i32 s5, s5, s4
	v_lshl_add_u32 v6, s5, 8, v4
	s_waitcnt lgkmcnt(0)
	v_ashrrev_i32_e32 v7, 31, v6
	v_lshlrev_b64 v[6:7], 6, v[6:7]
	v_lshl_add_u64 v[10:11], v[2:3], 0, v[6:7]
	global_load_dwordx4 v[46:49], v[10:11], off
	global_load_dwordx4 v[50:53], v[10:11], off offset:16
	s_add_u32 s8, s8, s14
	s_addc_u32 s9, s9, s55
.Lfrain_issued:
	s_waitcnt vmcnt(0)
	s_mov_b64 s[8:9], s[2:3]
	v_cmp_gt_i64_e32 vcc, s[8:9], v[140:141]
	s_mov_b64 s[10:11], -1
	s_cbranch_vccnz .Lfrain_done
	v_pk_add_f32 v[16:17], v[16:17], v[20:21]
	v_pk_add_f32 v[14:15], v[14:15], v[18:19]
	v_cmp_lt_i32_e32 vcc, v172, v171
	v_add_f32_e32 v6, v14, v15
	v_add_f32_e32 v7, v16, v17
	v_add_f32_e32 v6, v6, v7
	v_cndmask_b32_e32 v7, v170, v172, vcc
	v_lshlrev_b32_e32 v7, 2, v7
	ds_bpermute_b32 v7, v7, v6
	s_and_saveexec_b64 s[10:11], s[6:7]
	s_waitcnt lgkmcnt(0)
	v_add_f32_e32 v6, v6, v7
	v_fmamk_f32 v6, v6, 0x3a800000, v166
	v_rsq_f32_e32 v6, v6
	ds_write_b32 v5, v6
	s_or_b64 exec, exec, s[10:11]
	s_add_u32 s8, s8, s14
	s_addc_u32 s9, s9, s55
	v_cmp_gt_i64_e32 vcc, s[8:9], v[140:141]
	s_mov_b64 s[10:11], -1
	s_cbranch_vccnz .Lfrain_done
	v_pk_add_f32 v[24:25], v[24:25], v[28:29]
	v_pk_add_f32 v[22:23], v[22:23], v[26:27]
	v_cmp_lt_i32_e32 vcc, v172, v171
	v_add_f32_e32 v6, v22, v23
	v_add_f32_e32 v7, v24, v25
	v_add_f32_e32 v6, v6, v7
	v_cndmask_b32_e32 v7, v170, v172, vcc
	v_lshlrev_b32_e32 v7, 2, v7
	ds_bpermute_b32 v7, v7, v6
	s_and_saveexec_b64 s[10:11], s[6:7]
	s_waitcnt lgkmcnt(0)
	v_add_f32_e32 v6, v6, v7
	v_fmamk_f32 v6, v6, 0x3a800000, v166
	v_rsq_f32_e32 v6, v6
	ds_write_b32 v5, v6 offset:1024
	s_or_b64 exec, exec, s[10:11]
	s_add_u32 s8, s8, s14
	s_addc_u32 s9, s9, s55
	v_cmp_gt_i64_e32 vcc, s[8:9], v[140:141]
	s_mov_b64 s[10:11], -1
	s_cbranch_vccnz .Lfrain_done
	v_pk_add_f32 v[32:33], v[32:33], v[36:37]
	v_pk_add_f32 v[30:31], v[30:31], v[34:35]
	v_cmp_lt_i32_e32 vcc, v172, v171
	v_add_f32_e32 v6, v30, v31
	v_add_f32_e32 v7, v32, v33
	v_add_f32_e32 v6, v6, v7
	v_cndmask_b32_e32 v7, v170, v172, vcc
	v_lshlrev_b32_e32 v7, 2, v7
	ds_bpermute_b32 v7, v7, v6
	s_and_saveexec_b64 s[10:11], s[6:7]
	s_waitcnt lgkmcnt(0)
	v_add_f32_e32 v6, v6, v7
	v_fmamk_f32 v6, v6, 0x3a800000, v166
	v_rsq_f32_e32 v6, v6
	ds_write_b32 v5, v6 offset:2048
	s_or_b64 exec, exec, s[10:11]
	s_add_u32 s8, s8, s14
	s_addc_u32 s9, s9, s55
	v_cmp_gt_i64_e32 vcc, s[8:9], v[140:141]
	s_mov_b64 s[10:11], -1
	s_cbranch_vccnz .Lfrain_done
	v_pk_add_f32 v[40:41], v[40:41], v[44:45]
	v_pk_add_f32 v[38:39], v[38:39], v[42:43]
	v_cmp_lt_i32_e32 vcc, v172, v171
	v_add_f32_e32 v6, v38, v39
	v_add_f32_e32 v7, v40, v41
	v_add_f32_e32 v6, v6, v7
	v_cndmask_b32_e32 v7, v170, v172, vcc
	v_lshlrev_b32_e32 v7, 2, v7
	ds_bpermute_b32 v7, v7, v6
	s_and_saveexec_b64 s[10:11], s[6:7]
	s_waitcnt lgkmcnt(0)
	v_add_f32_e32 v6, v6, v7
	v_fmamk_f32 v6, v6, 0x3a800000, v166
	v_rsq_f32_e32 v6, v6
	ds_write_b32 v5, v6 offset:3072
	s_or_b64 exec, exec, s[10:11]
	s_add_u32 s8, s8, s14
	s_addc_u32 s9, s9, s55
	v_cmp_gt_i64_e32 vcc, s[8:9], v[140:141]
	s_mov_b64 s[10:11], -1
	s_cbranch_vccnz .Lfrain_done
	v_pk_add_f32 v[48:49], v[48:49], v[52:53]
	v_pk_add_f32 v[46:47], v[46:47], v[50:51]
	v_cmp_lt_i32_e32 vcc, v172, v171
	v_add_f32_e32 v6, v46, v47
	v_add_f32_e32 v7, v48, v49
	v_add_f32_e32 v6, v6, v7
	v_cndmask_b32_e32 v7, v170, v172, vcc
	v_lshlrev_b32_e32 v7, 2, v7
	ds_bpermute_b32 v7, v7, v6
	s_and_saveexec_b64 s[10:11], s[6:7]
	s_waitcnt lgkmcnt(0)
	v_add_f32_e32 v6, v6, v7
	v_fmamk_f32 v6, v6, 0x3a800000, v166
	v_rsq_f32_e32 v6, v6
	ds_write_b32 v5, v6 offset:4096
	s_or_b64 exec, exec, s[10:11]
	s_add_u32 s8, s8, s14
	s_addc_u32 s9, s9, s55
.Lfrain_done:
.LBB0_403:
	v_readlane_b32 s4, v254, 16
	v_readlane_b32 s5, v254, 17
	s_andn2_b64 vcc, exec, s[4:5]
	v_readfirstlane_b32 s6, v130
	s_waitcnt vmcnt(0) lgkmcnt(0)
	s_barrier
	s_cbranch_vccnz .LBB0_427
	v_lshlrev_b32_e32 v2, 4, v130
	v_add_u32_e32 v3, 0x2000, v2
	v_ashrrev_i32_e32 v4, 31, v3
	v_lshrrev_b32_e32 v4, 22, v4
	v_add_u32_e32 v4, v3, v4
	v_ashrrev_i32_e32 v10, 10, v4
	v_mul_i32_i24_e32 v4, 0x400, v10
	v_sub_u32_e32 v3, v3, v4
	v_lshrrev_b32_e32 v4, 4, v3
	v_bitop3_b32 v3, v4, v3, 32 bitop3:0x6c
	v_ashrrev_i32_e32 v4, 31, v3
	v_lshrrev_b32_e32 v4, 26, v4
	v_add_u32_e32 v4, v3, v4
	v_lshlrev_b32_e32 v5, 3, v10
	v_ashrrev_i32_e32 v11, 6, v4
	v_and_b32_e32 v5, -16, v5
	v_add_u32_e32 v5, v11, v5
	v_and_b32_e32 v6, 3, v11
	s_mov_b32 s8, 0x1fffe0
	v_lshrrev_b32_e32 v7, 2, v5
	v_lshlrev_b32_e32 v8, 1, v5
	v_and_b32_e32 v4, 0xc0, v4
	v_and_or_b32 v6, v5, s8, v6
	v_and_b32_e32 v7, 4, v7
	v_and_b32_e32 v8, 24, v8
	v_sub_u32_e32 v3, v3, v4
	v_or3_b32 v6, v6, v7, v8
	v_lshlrev_b32_e32 v7, 5, v10
	v_ashrrev_i16_sdwa v3, v169, sext(v3) dst_sel:DWORD dst_unused:UNUSED_PAD src0_sel:DWORD src1_sel:BYTE_0
	v_and_b32_e32 v7, 32, v7
	v_bfe_i32 v12, v3, 0, 16
	v_add_lshl_u32 v3, v7, v12, 1
	v_lshl_add_u32 v144, v6, 11, v3
	v_lshl_add_u32 v146, v5, 11, v3
	v_bfe_i32 v3, v130, 27, 1
	v_lshrrev_b32_e32 v3, 22, v3
	v_add_u32_e32 v3, v2, v3
	v_and_b32_e32 v3, 0xfffffc00, v3
	v_sub_u32_e32 v2, v2, v3
	v_lshrrev_b32_e32 v3, 4, v2
	v_ashrrev_i32_e32 v4, 31, v130
	v_bitop3_b32 v2, v3, v2, 32 bitop3:0x6c
	v_lshrrev_b32_e32 v4, 26, v4
	v_ashrrev_i32_e32 v3, 31, v2
	v_add_u32_e32 v4, v130, v4
	v_lshrrev_b32_e32 v3, 26, v3
	v_ashrrev_i32_e32 v14, 6, v4
	s_mul_i32 s40, s40, 0x500000
	v_add_u32_e32 v3, v2, v3
	v_lshlrev_b32_e32 v4, 3, v14
	s_add_u32 s4, s82, s40
	v_ashrrev_i32_e32 v13, 6, v3
	v_and_b32_e32 v4, -16, v4
	s_addc_u32 s5, s83, 0
	v_add_u32_e32 v4, v13, v4
	s_add_u32 s4, s4, 0x500000
	v_and_b32_e32 v5, 3, v13
	v_lshrrev_b32_e32 v6, 2, v4
	v_lshlrev_b32_e32 v7, 1, v4
	v_and_b32_e32 v3, 0xc0, v3
	s_addc_u32 s5, s5, 0
	s_ashr_i32 s19, s6, 6
	v_and_or_b32 v5, v4, s8, v5
	v_and_b32_e32 v6, 4, v6
	v_and_b32_e32 v7, 24, v7
	v_sub_u32_e32 v2, v2, v3
	s_ashr_i32 s7, s6, 8
	s_lshl_b32 s20, s19, 10
	v_or3_b32 v5, v5, v6, v7
	v_lshlrev_b32_e32 v6, 5, v14
	v_ashrrev_i16_sdwa v2, v169, sext(v2) dst_sel:DWORD dst_unused:UNUSED_PAD src0_sel:DWORD src1_sel:BYTE_0
	v_readlane_b32 s8, v254, 36
	v_and_b32_e32 v6, 32, v6
	v_bfe_i32 v15, v2, 0, 16
	v_readlane_b32 s9, v254, 37
	s_add_u32 s22, s4, s8
	v_add_lshl_u32 v2, v6, v15, 1
	s_addc_u32 s23, s5, s9
	s_add_i32 s31, s20, 0
	v_lshl_add_u32 v148, v5, 11, v2
	s_add_i32 m0, s31, 0x10000
	v_lshl_add_u32 v150, v4, 11, v2
	global_load_lds_dwordx4 v148, s[22:23]
	s_add_i32 m0, s31, 0x12000
	s_add_u32 s8, s22, 0x40000
	global_load_lds_dwordx4 v144, s[22:23]
	s_addc_u32 s9, s23, 0
	s_add_i32 m0, s31, 0x14000
	v_mov_b32_e32 v149, v135
	global_load_lds_dwordx4 v148, s[8:9]
	s_add_i32 m0, s31, 0x16000
	v_mov_b32_e32 v145, v135
	global_load_lds_dwordx4 v144, s[8:9]
	v_readlane_b32 s8, v254, 34
	v_readlane_b32 s9, v254, 35
	s_add_u32 s12, s78, s8
	s_addc_u32 s13, s79, s9
	s_add_i32 s35, s31, 0x2000
	s_mov_b32 m0, s31
	s_add_u32 s8, s12, 0x40000
	global_load_lds_dwordx4 v150, s[12:13]
	s_mov_b32 m0, s35
	s_addc_u32 s9, s13, 0
	s_add_i32 s38, s31, 0x4000
	global_load_lds_dwordx4 v146, s[12:13]
	s_mov_b32 m0, s38
	s_add_i32 s40, s31, 0x6000
	global_load_lds_dwordx4 v150, s[8:9]
	s_mov_b32 m0, s40
	v_mov_b32_e32 v151, v135
	global_load_lds_dwordx4 v146, s[8:9]
	v_mov_b32_e32 v147, v135
	s_cmp_eq_u32 s7, 1
	v_lshl_add_u64 v[8:9], s[22:23], 0, v[148:149]
	v_lshl_add_u64 v[6:7], s[22:23], 0, v[144:145]
	v_lshl_add_u64 v[2:3], s[12:13], 0, v[150:151]
	s_cselect_b64 s[8:9], -1, 0
	s_cmp_lg_u32 s7, 1
	v_lshl_add_u64 v[4:5], s[12:13], 0, v[146:147]
	s_cbranch_scc1 .LBB0_406
	s_barrier

.Lsync_last_1:
	s_or_b64 exec, exec, s[22:23]
	s_add_u32 s46, s8, 0x17202400
	s_addc_u32 s47, s9, 0
	v_mov_b32_e32 v7, 0
	v_mov_b32_e32 v8, 1
	global_atomic_add v7, v8, s[46:47]
	global_atomic_add v7, v8, s[46:47] offset:256
	global_atomic_add v7, v8, s[46:47] offset:512
	global_atomic_add v7, v8, s[46:47] offset:768
	global_atomic_add v7, v8, s[46:47] offset:1024
	global_atomic_add v7, v8, s[46:47] offset:1280
	global_atomic_add v7, v8, s[46:47] offset:1536
	global_atomic_add v7, v8, s[46:47] offset:1792
	global_atomic_add v7, v8, s[46:47] offset:2048
	global_atomic_add v7, v8, s[46:47] offset:2304
	global_atomic_add v7, v8, s[46:47] offset:2560
	global_atomic_add v7, v8, s[46:47] offset:2816
	global_atomic_add v7, v8, s[46:47] offset:3072
	global_atomic_add v7, v8, s[46:47] offset:3328
	global_atomic_add v7, v8, s[46:47] offset:3584
	global_atomic_add v7, v8, s[46:47] offset:3840
